# plus: rope/gq constants of sliding-window attention loaded once per tile; cross-attention head loop with 8-deep LDS fragment prefetch
# speedup vs baseline: 1.0129x; 1.0008x over previous
.LBB0_180:
	s_or_b64 exec, exec, s[0:1]
	v_and_b32_e32 v37, 64, v182
	v_ashrrev_i32_e32 v59, 6, v36
	v_bfe_u32 v51, v36, 4, 2
	v_and_b32_e32 v56, 15, v36
	v_xor_b32_e32 v36, 1, v182
	v_add_u32_e32 v37, 64, v37
	v_cmp_lt_i32_e32 vcc, v36, v37
	v_lshlrev_b32_e32 v2, 4, v59
	v_min_i32_e32 v57, 6, v59
	v_and_b32_e32 v57, -2, v57
	v_cndmask_b32_e32 v61, v182, v36, vcc
	v_xor_b32_e32 v36, 16, v182
	v_cmp_lt_i32_e32 vcc, v36, v37
	v_lshlrev_b32_e32 v111, 2, v51
	v_lshlrev_b32_e32 v68, 4, v57
	v_cndmask_b32_e32 v66, v182, v36, vcc
	v_xor_b32_e32 v36, 32, v182
	v_cmp_lt_i32_e32 vcc, v36, v37
	v_or_b32_e32 v38, v68, v111
	s_movk_i32 s3, 0x7e
	v_cndmask_b32_e32 v67, v182, v36, vcc
	v_cmp_eq_u32_e32 vcc, 1, v51
	v_or_b32_e32 v39, 2, v38
	v_add_u32_e32 v69, 16, v68
	v_cndmask_b32_e64 v36, 0, 1.0, vcc
	v_cmp_ne_u32_e32 vcc, 0, v51
	v_add_u32_e32 v70, 2, v57
	v_lshlrev_b32_e32 v71, 4, v70
	v_cndmask_b32_e32 v114, -1.0, v36, vcc
	v_or_b32_e32 v36, v2, v56
	v_add_u32_e32 v37, 0x80, v36
	v_cmp_gt_i32_e32 vcc, v38, v36
	v_cmp_le_i32_e64 s[0:1], v38, v37
	s_and_b64 s[0:1], vcc, s[0:1]
	v_cmp_lt_i32_e32 vcc, s84, v38
	s_or_b64 s[4:5], s[22:23], vcc
	s_and_b64 s[0:1], s[0:1], s[4:5]
	v_cmp_ge_i32_e32 vcc, v38, v36
	v_cmp_lt_i32_e64 s[4:5], v38, v37
	s_and_b64 s[4:5], vcc, s[4:5]
	v_cmp_lt_i32_e32 vcc, s3, v38
	v_writelane_b32 v243, s0, 12
	s_or_b64 s[6:7], s[22:23], vcc
	v_cmp_gt_i32_e32 vcc, v39, v36
	v_writelane_b32 v243, s1, 13
	s_and_b64 s[0:1], s[4:5], s[6:7]
	v_cmp_le_i32_e64 s[6:7], v39, v37
	s_and_b64 s[6:7], vcc, s[6:7]
	v_cmp_lt_i32_e32 vcc, s84, v39
	v_writelane_b32 v243, s0, 14
	s_or_b64 s[8:9], s[22:23], vcc
	v_or_b32_e32 v38, 3, v38
	v_writelane_b32 v243, s1, 15
	s_and_b64 s[0:1], s[6:7], s[8:9]
	v_cmp_gt_i32_e32 vcc, v38, v36
	v_cmp_le_i32_e64 s[8:9], v38, v37
	s_and_b64 s[8:9], vcc, s[8:9]
	v_cmp_lt_i32_e32 vcc, s84, v38
	v_writelane_b32 v243, s0, 16
	s_or_b64 s[10:11], s[22:23], vcc
	v_or_b32_e32 v38, v69, v111
	v_writelane_b32 v243, s1, 17
	s_and_b64 s[0:1], s[8:9], s[10:11]
	v_cmp_gt_i32_e32 vcc, v38, v36
	v_cmp_le_i32_e64 s[10:11], v38, v37
	s_and_b64 s[10:11], vcc, s[10:11]
	v_cmp_lt_i32_e32 vcc, s84, v38
	v_writelane_b32 v243, s0, 18
	s_or_b64 s[12:13], s[22:23], vcc
	v_cmp_ge_i32_e32 vcc, v38, v36
	v_writelane_b32 v243, s1, 19
	s_and_b64 s[0:1], s[10:11], s[12:13]
	v_cmp_lt_i32_e64 s[12:13], v38, v37
	s_and_b64 s[12:13], vcc, s[12:13]
	v_cmp_lt_i32_e32 vcc, s3, v38
	v_writelane_b32 v243, s0, 20
	s_or_b64 s[14:15], s[22:23], vcc
	v_or_b32_e32 v39, 2, v38
	v_writelane_b32 v243, s1, 21
	s_and_b64 s[0:1], s[12:13], s[14:15]
	v_cmp_gt_i32_e32 vcc, v39, v36
	v_cmp_le_i32_e64 s[14:15], v39, v37
	s_and_b64 s[14:15], vcc, s[14:15]
	v_cmp_lt_i32_e32 vcc, s84, v39
	v_writelane_b32 v243, s0, 22
	s_or_b64 s[16:17], s[22:23], vcc
	v_or_b32_e32 v38, 3, v38
	v_writelane_b32 v243, s1, 23
	s_and_b64 s[0:1], s[14:15], s[16:17]
	v_cmp_gt_i32_e32 vcc, v38, v36
	v_cmp_le_i32_e64 s[16:17], v38, v37
	s_and_b64 s[16:17], vcc, s[16:17]
	v_cmp_lt_i32_e32 vcc, s84, v38
	v_writelane_b32 v243, s0, 24
	s_or_b64 s[18:19], s[22:23], vcc
	v_or_b32_e32 v38, v71, v111
	v_writelane_b32 v243, s1, 25
	s_and_b64 s[0:1], s[16:17], s[18:19]
	v_cmp_gt_i32_e32 vcc, v38, v36
	v_cmp_le_i32_e64 s[18:19], v38, v37
	s_and_b64 s[18:19], vcc, s[18:19]
	v_cmp_lt_i32_e32 vcc, s84, v38
	v_writelane_b32 v243, s0, 26
	s_mov_b32 s4, s20
	s_or_b64 s[20:21], s[22:23], vcc
	v_writelane_b32 v243, s1, 27
	s_and_b64 s[0:1], s[18:19], s[20:21]
	v_cmp_ge_i32_e32 vcc, v38, v36
	v_cmp_lt_i32_e64 s[20:21], v38, v37
	s_and_b64 s[20:21], vcc, s[20:21]
	v_cmp_lt_i32_e32 vcc, s3, v38
	s_mov_b64 s[6:7], s[22:23]
	s_or_b64 s[22:23], s[22:23], vcc
	v_or_b32_e32 v39, 2, v38
	s_and_b64 s[20:21], s[20:21], s[22:23]
	v_cmp_gt_i32_e32 vcc, v39, v36
	v_cmp_le_i32_e64 s[22:23], v39, v37
	s_and_b64 s[22:23], vcc, s[22:23]
	v_cmp_lt_i32_e32 vcc, s84, v39
	s_or_b64 s[24:25], s[6:7], vcc
	v_or_b32_e32 v38, 3, v38
	s_and_b64 s[22:23], s[22:23], s[24:25]
	v_cmp_gt_i32_e32 vcc, v38, v36
	v_cmp_le_i32_e64 s[24:25], v38, v37
	v_add_u32_e32 v72, 48, v68
	s_and_b64 s[24:25], vcc, s[24:25]
	v_cmp_lt_i32_e32 vcc, s84, v38
	s_or_b64 s[26:27], s[6:7], vcc
	v_or_b32_e32 v38, v72, v111
	s_and_b64 s[24:25], s[24:25], s[26:27]
	v_cmp_gt_i32_e32 vcc, v38, v36
	v_cmp_le_i32_e64 s[26:27], v38, v37
	s_and_b64 s[26:27], vcc, s[26:27]
	v_cmp_lt_i32_e32 vcc, s84, v38
	s_or_b64 s[28:29], s[6:7], vcc
	s_and_b64 s[26:27], s[26:27], s[28:29]
	v_cmp_ge_i32_e32 vcc, v38, v36
	v_cmp_lt_i32_e64 s[28:29], v38, v37
	s_and_b64 s[28:29], vcc, s[28:29]
	v_cmp_lt_i32_e32 vcc, s3, v38
	s_or_b64 s[30:31], s[6:7], vcc
	v_or_b32_e32 v39, 2, v38
	s_and_b64 s[28:29], s[28:29], s[30:31]
	v_cmp_gt_i32_e32 vcc, v39, v36
	v_cmp_le_i32_e64 s[30:31], v39, v37
	s_and_b64 s[30:31], vcc, s[30:31]
	v_cmp_lt_i32_e32 vcc, s84, v39
	s_or_b64 s[34:35], s[6:7], vcc
	v_or_b32_e32 v38, 3, v38
	v_add_u32_e32 v73, 4, v57
	s_and_b64 s[30:31], s[30:31], s[34:35]
	v_cmp_gt_i32_e32 vcc, v38, v36
	v_cmp_le_i32_e64 s[34:35], v38, v37
	v_lshlrev_b32_e32 v74, 4, v73
	s_and_b64 s[34:35], vcc, s[34:35]
	v_cmp_lt_i32_e32 vcc, s84, v38
	s_or_b64 s[36:37], s[6:7], vcc
	v_or_b32_e32 v38, v74, v111
	s_and_b64 s[34:35], s[34:35], s[36:37]
	v_cmp_gt_i32_e32 vcc, v38, v36
	v_cmp_le_i32_e64 s[36:37], v38, v37
	s_and_b64 s[36:37], vcc, s[36:37]
	v_cmp_lt_i32_e32 vcc, s84, v38
	s_or_b64 s[38:39], s[6:7], vcc
	s_and_b64 s[36:37], s[36:37], s[38:39]
	v_cmp_ge_i32_e32 vcc, v38, v36
	v_cmp_lt_i32_e64 s[38:39], v38, v37
	s_and_b64 s[38:39], vcc, s[38:39]
	v_cmp_lt_i32_e32 vcc, s3, v38
	s_or_b64 s[40:41], s[6:7], vcc
	v_or_b32_e32 v39, 2, v38
	s_and_b64 s[38:39], s[38:39], s[40:41]
	v_cmp_gt_i32_e32 vcc, v39, v36
	v_cmp_le_i32_e64 s[40:41], v39, v37
	s_and_b64 s[40:41], vcc, s[40:41]
	v_cmp_lt_i32_e32 vcc, s84, v39
	s_or_b64 s[42:43], s[6:7], vcc
	v_or_b32_e32 v38, 3, v38
	s_and_b64 s[40:41], s[40:41], s[42:43]
	v_cmp_gt_i32_e32 vcc, v38, v36
	v_cmp_le_i32_e64 s[42:43], v38, v37
	v_add_u32_e32 v75, 0x50, v68
	s_and_b64 s[42:43], vcc, s[42:43]
	v_cmp_lt_i32_e32 vcc, s84, v38
	s_or_b64 s[44:45], s[6:7], vcc
	v_or_b32_e32 v38, v75, v111
	s_and_b64 s[42:43], s[42:43], s[44:45]
	v_cmp_gt_i32_e32 vcc, v38, v36
	v_cmp_le_i32_e64 s[44:45], v38, v37
	s_and_b64 s[44:45], vcc, s[44:45]
	v_cmp_lt_i32_e32 vcc, s84, v38
	s_or_b64 s[46:47], s[6:7], vcc
	s_and_b64 s[44:45], s[44:45], s[46:47]
	v_cmp_ge_i32_e32 vcc, v38, v36
	v_cmp_lt_i32_e64 s[46:47], v38, v37
	s_and_b64 s[46:47], vcc, s[46:47]
	v_cmp_lt_i32_e32 vcc, s3, v38
	s_or_b64 s[48:49], s[6:7], vcc
	v_or_b32_e32 v39, 2, v38
	s_and_b64 s[46:47], s[46:47], s[48:49]
	v_cmp_gt_i32_e32 vcc, v39, v36
	v_cmp_le_i32_e64 s[48:49], v39, v37
	s_and_b64 s[48:49], vcc, s[48:49]
	v_cmp_lt_i32_e32 vcc, s84, v39
	s_or_b64 s[50:51], s[6:7], vcc
	v_or_b32_e32 v38, 3, v38
	v_add_u32_e32 v76, 6, v57
	s_and_b64 s[48:49], s[48:49], s[50:51]
	v_cmp_gt_i32_e32 vcc, v38, v36
	v_cmp_le_i32_e64 s[50:51], v38, v37
	v_lshlrev_b32_e32 v77, 4, v76
	s_and_b64 s[50:51], vcc, s[50:51]
	v_cmp_lt_i32_e32 vcc, s84, v38
	s_or_b64 s[52:53], s[6:7], vcc
	v_or_b32_e32 v38, v77, v111
	s_and_b64 s[50:51], s[50:51], s[52:53]
	v_cmp_gt_i32_e32 vcc, v38, v36
	v_cmp_le_i32_e64 s[52:53], v38, v37
	s_and_b64 s[52:53], vcc, s[52:53]
	v_cmp_lt_i32_e32 vcc, s84, v38
	s_or_b64 s[54:55], s[6:7], vcc
	s_and_b64 s[52:53], s[52:53], s[54:55]
	v_cmp_ge_i32_e32 vcc, v38, v36
	v_cmp_lt_i32_e64 s[54:55], v38, v37
	s_and_b64 s[54:55], vcc, s[54:55]
	v_cmp_lt_i32_e32 vcc, s3, v38
	s_or_b64 s[56:57], s[6:7], vcc
	v_or_b32_e32 v39, 2, v38
	s_and_b64 s[54:55], s[54:55], s[56:57]
	v_cmp_gt_i32_e32 vcc, v39, v36
	v_cmp_le_i32_e64 s[56:57], v39, v37
	s_and_b64 s[56:57], vcc, s[56:57]
	v_cmp_lt_i32_e32 vcc, s84, v39
	s_or_b64 s[58:59], s[6:7], vcc
	v_or_b32_e32 v38, 3, v38
	s_and_b64 s[56:57], s[56:57], s[58:59]
	v_cmp_gt_i32_e32 vcc, v38, v36
	v_cmp_le_i32_e64 s[58:59], v38, v37
	v_add_u32_e32 v78, 0x70, v68
	s_and_b64 s[58:59], vcc, s[58:59]
	v_cmp_lt_i32_e32 vcc, s84, v38
	s_or_b64 s[60:61], s[6:7], vcc
	v_or_b32_e32 v38, v78, v111
	s_and_b64 s[58:59], s[58:59], s[60:61]
	v_cmp_gt_i32_e32 vcc, v38, v36
	v_cmp_le_i32_e64 s[60:61], v38, v37
	s_and_b64 s[60:61], vcc, s[60:61]
	v_cmp_lt_i32_e32 vcc, s84, v38
	s_or_b64 s[62:63], s[6:7], vcc
	s_and_b64 s[60:61], s[60:61], s[62:63]
	v_cmp_ge_i32_e32 vcc, v38, v36
	v_cmp_lt_i32_e64 s[62:63], v38, v37
	s_and_b64 s[62:63], vcc, s[62:63]
	v_cmp_lt_i32_e32 vcc, s3, v38
	s_or_b64 s[64:65], s[6:7], vcc
	v_or_b32_e32 v39, 2, v38
	s_and_b64 s[62:63], s[62:63], s[64:65]
	v_cmp_gt_i32_e32 vcc, v39, v36
	v_cmp_le_i32_e64 s[64:65], v39, v37
	s_and_b64 s[64:65], vcc, s[64:65]
	v_cmp_lt_i32_e32 vcc, s84, v39
	s_or_b64 s[66:67], s[6:7], vcc
	v_or_b32_e32 v38, 3, v38
	s_and_b64 s[64:65], s[64:65], s[66:67]
	v_cmp_gt_i32_e32 vcc, v38, v36
	v_cmp_le_i32_e64 s[66:67], v38, v37
	v_add_u32_e32 v79, 8, v57
	s_and_b64 s[66:67], vcc, s[66:67]
	v_cmp_lt_i32_e32 vcc, s84, v38
	v_lshlrev_b32_e32 v98, 4, v79
	s_or_b64 s[68:69], s[6:7], vcc
	v_or_b32_e32 v38, v98, v111
	s_and_b64 s[66:67], s[66:67], s[68:69]
	v_cmp_gt_i32_e32 vcc, v38, v36
	v_cmp_le_i32_e64 s[68:69], v38, v37
	s_and_b64 s[68:69], vcc, s[68:69]
	v_cmp_lt_i32_e32 vcc, s84, v38
	s_or_b64 s[70:71], s[6:7], vcc
	s_and_b64 s[68:69], s[68:69], s[70:71]
	v_cmp_ge_i32_e32 vcc, v38, v36
	v_cmp_lt_i32_e64 s[70:71], v38, v37
	s_and_b64 s[70:71], vcc, s[70:71]
	v_cmp_lt_i32_e32 vcc, s3, v38
	s_or_b64 s[72:73], s[6:7], vcc
	v_or_b32_e32 v39, 2, v38
	s_and_b64 s[70:71], s[70:71], s[72:73]
	v_cmp_gt_i32_e32 vcc, v39, v36
	v_cmp_le_i32_e64 s[72:73], v39, v37
	s_and_b64 s[72:73], vcc, s[72:73]
	v_cmp_lt_i32_e32 vcc, s84, v39
	s_or_b64 s[74:75], s[6:7], vcc
	v_or_b32_e32 v38, 3, v38
	s_and_b64 s[72:73], s[72:73], s[74:75]
	v_cmp_gt_i32_e32 vcc, v38, v36
	v_cmp_le_i32_e64 s[74:75], v38, v37
	s_and_b64 s[74:75], vcc, s[74:75]
	v_cmp_lt_i32_e32 vcc, s84, v38
	v_add_u32_e32 v99, 0x90, v68
	s_or_b64 s[76:77], s[6:7], vcc
	v_or_b32_e32 v38, v99, v111
	s_and_b64 s[74:75], s[74:75], s[76:77]
	v_cmp_gt_i32_e32 vcc, v38, v36
	v_cmp_le_i32_e64 s[76:77], v38, v37
	s_and_b64 s[76:77], vcc, s[76:77]
	v_cmp_lt_i32_e32 vcc, s84, v38
	s_or_b64 s[78:79], s[6:7], vcc
	s_and_b64 s[76:77], s[76:77], s[78:79]
	v_cmp_ge_i32_e32 vcc, v38, v36
	v_cmp_lt_i32_e64 s[78:79], v38, v37
	s_and_b64 s[78:79], vcc, s[78:79]
	v_cmp_lt_i32_e32 vcc, s3, v38
	s_or_b64 s[80:81], s[6:7], vcc
	v_or_b32_e32 v39, 2, v38
	s_and_b64 s[78:79], s[78:79], s[80:81]
	v_cmp_gt_i32_e32 vcc, v39, v36
	v_cmp_le_i32_e64 s[80:81], v39, v37
	s_and_b64 s[80:81], vcc, s[80:81]
	v_cmp_lt_i32_e32 vcc, s84, v39
	s_or_b64 s[82:83], s[6:7], vcc
	v_writelane_b32 v243, s6, 28
	v_or_b32_e32 v38, 3, v38
	v_add_u32_e32 v64, s2, v50
	v_writelane_b32 v243, s7, 29
	v_add_u32_e32 v90, s2, v2
	s_mov_b32 s2, s4
	v_add_u32_e32 v2, s4, v2
	s_and_b64 s[80:81], s[80:81], s[82:83]
	v_cmp_gt_i32_e32 vcc, v38, v36
	v_cmp_le_i32_e64 s[82:83], v38, v37
	v_writelane_b32 v243, s2, 30
	v_or_b32_e32 v80, v2, v56
	v_lshlrev_b32_e32 v58, 3, v51
	v_mov_b64_e32 v[36:37], s[88:89]
	v_writelane_b32 v243, s3, 31
	v_mad_i64_i32 v[82:83], s[2:3], v80, s92, v[36:37]
	v_lshlrev_b32_e32 v2, 4, v51
	v_bitop3_b32 v60, v58, 8, v58 bitop3:0xc
	v_lshl_add_u64 v[36:37], v[82:83], 0, v[2:3]
	v_lshlrev_b32_e32 v44, 1, v60
	v_mov_b32_e32 v45, v3
	s_and_b64 s[82:83], vcc, s[82:83]
	v_cmp_lt_i32_e32 vcc, s84, v38
	global_load_dwordx4 v[40:43], v[36:37], off offset:2048
	s_nop 0
	global_load_dwordx4 v[36:39], v[36:37], off offset:2112
	v_lshl_add_u64 v[44:45], v[82:83], 0, v[44:45]
	global_load_dwordx4 v[44:47], v[44:45], off offset:2048
	v_mul_lo_u32 v59, v59, s93
	v_add_u32_e32 v59, s96, v59
	v_mul_u32_u24_e32 v100, 0x210, v56
	v_add3_u32 v109, v59, v100, v58
	v_mul_lo_u32 v59, v50, s97
	v_add_u32_e32 v62, 0, v59
	v_lshl_add_u32 v115, v55, 1, v62
	v_mad_u64_u32 v[62:63], s[2:3], v50, s98, v[62:63]
	v_lshl_add_u64 v[52:53], s[88:89], 0, v[52:53]
	s_mov_b32 s2, 0xfff70b80
	v_lshl_add_u64 v[52:53], v[48:49], 1, v[52:53]
	s_mov_b32 s3, -1
	v_lshl_add_u64 v[86:87], v[52:53], 0, s[2:3]
	s_mov_b32 s2, 0xfff70a80
	s_mov_b32 s3, -1
	v_max_i32_e32 v50, 0x80, v64
	v_lshl_add_u64 v[88:89], v[52:53], 0, s[2:3]
	v_or_b32_e32 v52, v90, v56
	v_lshl_add_u32 v64, v50, 4, v183
	v_lshlrev_b32_e32 v52, 4, v52
	s_or_b64 s[84:85], s[6:7], vcc
	v_ashrrev_i32_e32 v65, 31, v64
	v_ashrrev_i32_e32 v53, 31, v52
	s_and_b64 s[82:83], s[82:83], s[84:85]
	v_lshl_add_u64 v[84:85], v[64:65], 2, s[86:87]
	v_lshl_add_u64 v[90:91], v[52:53], 2, s[86:87]
	s_mov_b32 s2, s96
	v_readlane_b32 s84, v244, 10
	v_readlane_b32 s88, v244, 14
	v_readlane_b32 s89, v244, 15
	v_readlane_b32 s90, v244, 16
	v_readlane_b32 s91, v244, 17
	v_readlane_b32 s92, v244, 18
	v_readlane_b32 s93, v244, 19
	v_readlane_b32 s94, v244, 20
	v_readlane_b32 s95, v244, 21
	v_readlane_b32 s96, v244, 22
	v_readlane_b32 s97, v244, 23
	s_mov_b64 s[8:9], s[88:89]
	v_add_u32_e32 v52, 0, v2
	s_mov_b64 s[12:13], s[92:93]
	v_lshlrev_b32_e32 v2, 5, v51
	v_lshl_add_u64 v[94:95], s[12:13], 0, v[2:3]
	v_lshlrev_b32_e32 v2, 2, v60
	s_mov_b64 s[10:11], s[90:91]
	s_mov_b64 s[14:15], s[94:95]
	s_mov_b64 s[16:17], s[96:97]
	s_movk_i32 s97, 0x90
	v_lshl_add_u64 v[96:97], s[12:13], 0, v[2:3]
	v_or_b32_e32 v2, v68, v56
	v_lshl_add_u64 v[92:93], v[48:49], 2, s[14:15]
	v_mul_lo_u32 v48, v2, s97
	v_or_b32_e32 v2, v69, v56
	v_mul_lo_u32 v49, v2, s97
	v_or_b32_e32 v2, v71, v56
	v_mul_lo_u32 v55, v2, s97
	v_or_b32_e32 v2, v72, v56
	v_mul_lo_u32 v59, v2, s97
	v_or_b32_e32 v2, v74, v56
	v_lshlrev_b32_e32 v129, 2, v61
	v_mul_lo_u32 v61, v2, s97
	v_or_b32_e32 v2, v75, v56
	v_mul_lo_u32 v63, v2, s97
	v_or_b32_e32 v2, v77, v56
	v_mul_lo_u32 v64, v2, s97
	v_or_b32_e32 v2, v78, v56
	v_mul_lo_u32 v65, v2, s97
	v_or_b32_e32 v2, v98, v56
	v_lshlrev_b32_e32 v128, 2, v66
	v_mov_b32_e32 v53, v52
	v_mul_lo_u32 v66, v2, s97
	v_or_b32_e32 v2, v99, v56
	v_mul_u32_u24_e32 v50, 0x4200, v54
	v_lshlrev_b32_e32 v113, 2, v67
	v_readlane_b32 s85, v244, 11
	v_readlane_b32 s86, v244, 12
	v_readlane_b32 s87, v244, 13
	v_readlane_b32 s98, v244, 24
	v_mul_lo_u32 v56, v2, s97
	v_lshl_add_u32 v57, v57, 5, v53
	v_lshl_add_u32 v67, v70, 5, v53
	v_lshl_add_u32 v68, v73, 5, v53
	v_lshl_add_u32 v69, v76, 5, v53
	v_lshl_add_u32 v53, v79, 5, v53
	v_ashrrev_i32_e32 v81, 31, v80
	v_readlane_b32 s99, v244, 25
	s_movk_i32 s98, 0xff72
	s_mov_b32 s96, s2
	s_movk_i32 s93, 0x2100
	s_movk_i32 s92, 0x1200
	v_and_b32_e32 v241, 24, v62
	v_and_b32_e32 v242, 32, v62
	v_and_b32_e32 v62, 0xffffffc7, v62
	v_lshlrev_b32_e32 v241, 1, v241
	v_lshrrev_b32_e32 v242, 2, v242
	v_or3_b32 v62, v62, v241, v242
	v_add_u32_e32 v116, v62, v50
	v_lshlrev_b32_e32 v2, 1, v60
	v_lshlrev_b32_e32 v98, 1, v58
	v_add_u32_e32 v117, v52, v48
	v_add_u32_e32 v118, v52, v49
	v_add_u32_e32 v119, v52, v55
	v_add_u32_e32 v120, v52, v59
	v_add_u32_e32 v121, v52, v61
	v_add_u32_e32 v122, v52, v63
	v_add_u32_e32 v123, v52, v64
	v_add_u32_e32 v124, v52, v65
	v_add_u32_e32 v125, v52, v66
	v_add_u32_e32 v126, v52, v56
	v_add_u32_e32 v127, v57, v100
	v_add_u32_e32 v130, v67, v100
	v_add_u32_e32 v131, v68, v100
	v_add_u32_e32 v132, v69, v100
	v_add_u32_e32 v133, v53, v100
	v_cmp_eq_u32_e64 s[84:85], 0, v54
	v_cmp_gt_u32_e64 s[86:87], 2, v51
	global_load_dwordx4 v[224:227], v[94:95], off
	global_load_dwordx4 v[228:231], v[94:95], off offset:16
	global_load_dwordx4 v[232:235], v[94:95], off offset:128
	global_load_dwordx4 v[236:239], v[94:95], off offset:144
	global_load_dwordx4 v[248:251], v[90:91], off offset:32
	global_load_dwordx4 v[252:255], v[90:91], off offset:48
	v_mov_b32_e32 v240, 1.0
	v_mov_b32_e32 v241, 1.0
	v_mov_b32_e32 v242, 1.0
	v_mov_b32_e32 v245, 1.0
	v_mov_b32_e32 v246, 1.0
	v_mov_b32_e32 v247, 1.0
	v_mov_b32_e32 v217, 1.0
	v_mov_b32_e32 v219, 1.0
	s_and_saveexec_b64 vcc, s[86:87]
	global_load_dword v240, v[90:91], off
	global_load_dword v241, v[90:91], off offset:4
	global_load_dword v242, v[90:91], off offset:8
	global_load_dword v245, v[90:91], off offset:12
	global_load_dword v246, v[90:91], off offset:16
	global_load_dword v247, v[90:91], off offset:20
	global_load_dword v217, v[90:91], off offset:24
	global_load_dword v219, v[90:91], off offset:28
	s_or_b64 exec, exec, vcc
	s_mov_b64 s[2:3], -1
	s_branch .LBB0_182

.LBB0_188:
	global_load_dword v79, v[96:97], off
	global_load_dwordx4 v[64:67], v[96:97], off offset:4
	global_load_dwordx3 v[76:78], v[96:97], off offset:20
	s_xor_b64 s[88:89], s[2:3], -1
	s_mov_b32 s90, 0
	s_mov_b64 s[2:3], -1
	v_mul_f32_e32 v102, v114, v248
	v_mul_f32_e32 v103, v114, v249
	v_mul_f32_e32 v104, v114, v250
	v_mul_f32_e32 v105, v114, v251
	v_mul_f32_e32 v106, v114, v252
	v_mul_f32_e32 v107, v114, v253
	v_mul_f32_e32 v108, v114, v254
	v_mul_f32_e32 v101, v114, v255
	s_branch .LBB0_190

.LBB0_190:
	v_lshlrev_b32_e32 v100, 16, v36
	v_and_b32_e32 v99, 0xffff0000, v36
	v_lshlrev_b32_e32 v134, 16, v40
	v_and_b32_e32 v135, 0xffff0000, v40
	v_mul_f32_e32 v68, v100, v100
	v_mul_f32_e32 v140, v99, v99
	v_lshlrev_b32_e32 v75, 16, v37
	v_fmac_f32_e32 v68, v134, v134
	v_fmac_f32_e32 v140, v135, v135
	v_lshlrev_b32_e32 v136, 16, v41
	v_add_f32_e32 v68, v68, v140
	v_mul_f32_e32 v140, v75, v75
	v_and_b32_e32 v74, 0xffff0000, v37
	v_fmac_f32_e32 v140, v136, v136
	v_and_b32_e32 v137, 0xffff0000, v41
	v_add_f32_e32 v68, v140, v68
	v_mul_f32_e32 v140, v74, v74
	v_lshlrev_b32_e32 v73, 16, v38
	v_fmac_f32_e32 v140, v137, v137
	v_lshlrev_b32_e32 v138, 16, v42
	v_add_f32_e32 v68, v140, v68
	v_mul_f32_e32 v140, v73, v73
	v_and_b32_e32 v72, 0xffff0000, v38
	v_fmac_f32_e32 v140, v138, v138
	v_and_b32_e32 v139, 0xffff0000, v42
	v_add_f32_e32 v68, v140, v68
	v_mul_f32_e32 v140, v72, v72
	v_lshlrev_b32_e32 v71, 16, v39
	v_fmac_f32_e32 v140, v139, v139
	v_lshlrev_b32_e32 v142, 16, v43
	v_add_f32_e32 v68, v140, v68
	v_mul_f32_e32 v140, v71, v71
	v_and_b32_e32 v70, 0xffff0000, v39
	v_fmac_f32_e32 v140, v142, v142
	v_and_b32_e32 v69, 0xffff0000, v43
	v_add_f32_e32 v68, v140, v68
	v_mul_f32_e32 v140, v70, v70
	v_fmac_f32_e32 v140, v69, v69
	v_add_f32_e32 v68, v140, v68
	ds_bpermute_b32 v140, v128, v68
	v_mov_b32_e32 v141, v241
	s_waitcnt lgkmcnt(0)
	v_add_f32_e32 v145, v68, v140
	ds_bpermute_b32 v146, v113, v145
	v_mov_b32_e32 v140, v240
	v_mov_b32_e32 v143, v242
	v_mov_b32_e32 v144, v245
	v_mov_b32_e32 v147, v246
	v_mov_b32_e32 v148, v247
	v_mov_b32_e32 v149, v217
	v_mov_b32_e32 v68, v219
	s_waitcnt lgkmcnt(0)
	v_add_f32_e32 v145, v145, v146
	v_fmamk_f32 v145, v145, 0x3c800000, v180
	v_rsq_f32_e32 v145, v145
	v_lshlrev_b32_e32 v146, 16, v47
	v_readlane_b32 s4, v244, 62
	v_readlane_b32 s5, v244, 63
	v_mul_f32_e32 v145, 0x3e38aa3b, v145
	v_mul_f32_e32 v146, v145, v146
	v_mul_f32_e32 v142, v145, v142
	s_waitcnt vmcnt(0)
	v_mul_f32_e32 v146, v146, v77
	v_mul_f32_e32 v142, v230, v142
	v_mul_f32_e32 v146, v108, v146
	v_fmac_f32_e32 v146, v142, v149
	v_and_b32_e32 v142, 0xffff0000, v46
	v_mul_f32_e32 v142, v145, v142
	v_mul_f32_e32 v139, v145, v139
	v_mul_f32_e32 v142, v142, v76
	v_mul_f32_e32 v139, v229, v139
	v_mul_f32_e32 v142, v107, v142
	v_fmac_f32_e32 v142, v139, v148
	v_lshlrev_b32_e32 v139, 16, v46
	v_mul_f32_e32 v139, v145, v139
	v_mul_f32_e32 v138, v145, v138
	v_mul_f32_e32 v139, v139, v67
	v_mul_f32_e32 v138, v228, v138
	v_mul_f32_e32 v139, v106, v139
	v_fmac_f32_e32 v139, v138, v147
	v_and_b32_e32 v138, 0xffff0000, v45
	v_mul_f32_e32 v138, v145, v138
	v_mul_f32_e32 v137, v145, v137
	v_mul_f32_e32 v138, v138, v66
	v_mul_f32_e32 v137, v227, v137
	v_mul_f32_e32 v138, v105, v138
	v_fmac_f32_e32 v138, v137, v144
	v_lshlrev_b32_e32 v137, 16, v45
	v_mul_f32_e32 v137, v145, v137
	v_mul_f32_e32 v136, v145, v136
	v_mul_f32_e32 v137, v137, v65
	v_mul_f32_e32 v136, v226, v136
	v_mul_f32_e32 v137, v104, v137
	v_fmac_f32_e32 v137, v136, v143
	v_and_b32_e32 v136, 0xffff0000, v44
	v_mul_f32_e32 v136, v145, v136
	v_mul_f32_e32 v135, v145, v135
	v_mul_f32_e32 v136, v136, v64
	v_mul_f32_e32 v135, v225, v135
	v_mul_f32_e32 v136, v103, v136
	v_fmac_f32_e32 v136, v135, v141
	v_lshlrev_b32_e32 v135, 16, v44
	v_mul_f32_e32 v135, v145, v135
	v_mul_f32_e32 v134, v145, v134
	v_mul_f32_e32 v135, v135, v79
	v_mul_f32_e32 v134, v224, v134
	v_mul_f32_e32 v135, v102, v135
	v_mul_f32_e32 v100, v145, v100
	v_mul_f32_e32 v69, v145, v69
	v_fmac_f32_e32 v135, v134, v140
	v_mul_f32_e32 v134, v232, v100
	v_mul_f32_e32 v100, v231, v69
	v_mul_f32_e32 v69, v145, v70
	v_mul_f32_e32 v147, v239, v69
	v_and_b32_e32 v69, 0xffff0000, v47
	v_mul_f32_e32 v69, v145, v69
	v_mul_f32_e32 v69, v69, v78
	v_mul_f32_e32 v71, v145, v71
	v_pk_mul_f32 v[68:69], v[100:101], v[68:69]
	s_or_b32 s90, s90, s33
	v_mul_f32_e32 v99, v145, v99
	v_mul_f32_e32 v75, v145, v75
	v_mul_f32_e32 v74, v145, v74
	v_mul_f32_e32 v73, v145, v73
	v_mul_f32_e32 v72, v145, v72
	v_mul_f32_e32 v71, v238, v71
	v_add_f32_e32 v68, v68, v69
	s_mov_b32 s91, s5
	s_cmp_eq_u32 s90, 3
	v_mul_f32_e32 v99, v233, v99
	v_mul_f32_e32 v140, v234, v75
	v_mul_f32_e32 v141, v235, v74
	v_mul_f32_e32 v143, v236, v73
	v_mul_f32_e32 v144, v237, v72
	v_cvt_pk_bf16_f32 v72, v135, v136
	v_cvt_pk_bf16_f32 v73, v137, v138
	v_cvt_pk_bf16_f32 v74, v139, v142
	v_cvt_pk_bf16_f32 v75, v146, v68
	v_cvt_pk_bf16_f32 v68, v134, v99
	v_cvt_pk_bf16_f32 v69, v140, v141
	v_cvt_pk_bf16_f32 v70, v143, v144
	v_cvt_pk_bf16_f32 v71, v71, v147
	s_cbranch_scc1 .LBB0_189
	s_lshl_b32 s94, s90, 7
	s_mov_b32 s95, s91
	v_lshl_add_u64 v[36:37], v[82:83], 0, s[94:95]
	v_mov_b32_e32 v99, v3
	v_lshl_add_u64 v[44:45], v[36:37], 0, v[2:3]
	v_lshl_add_u64 v[40:41], v[36:37], 0, v[98:99]
	global_load_dwordx4 v[36:39], v[40:41], off offset:2240
	s_nop 0
	global_load_dwordx4 v[40:43], v[40:41], off offset:2176
	s_nop 0
	global_load_dwordx4 v[44:47], v[44:45], off offset:2176
	s_branch .LBB0_189
.LBB0_208:
	s_waitcnt vmcnt(0)
	v_lshlrev_b32_e32 v2, 1, v111
	v_lshl_add_u64 v[14:15], v[82:83], 0, v[2:3]
	global_load_dwordx2 v[20:21], v[14:15], off offset:3072
	v_readlane_b32 s8, v244, 0
	v_lshlrev_b32_e32 v18, 2, v111
	v_readlane_b32 s12, v244, 4
	v_readlane_b32 s13, v244, 5
	ds_bpermute_b32 v16, v128, v110
	v_readlane_b32 s4, v244, 57
	v_lshlrev_b64 v[12:13], 11, v[80:81]
	v_readlane_b32 s6, v244, 59
	v_readlane_b32 s7, v244, 60
	global_load_dwordx4 v[8:11], v18, s[12:13] offset:2048
	global_load_dwordx2 v[46:47], v[14:15], off offset:3104
	global_load_dwordx2 v[52:53], v[14:15], off offset:3136
	global_load_dwordx2 v[54:55], v[14:15], off offset:3168
	global_load_dwordx4 v[56:59], v18, s[12:13] offset:2112
	global_load_dwordx4 v[60:63], v18, s[12:13] offset:2176
	global_load_dwordx4 v[64:67], v18, s[12:13] offset:2240
	global_load_dwordx2 v[68:69], v[14:15], off offset:3200
	global_load_dwordx4 v[70:73], v18, s[12:13] offset:2304
	global_load_dwordx2 v[74:75], v[14:15], off offset:3232
	global_load_dwordx2 v[76:77], v[14:15], off offset:3264
	global_load_dwordx2 v[78:79], v[14:15], off offset:3296
	global_load_dwordx4 v[84:87], v18, s[12:13] offset:2368
	global_load_dwordx4 v[88:91], v18, s[12:13] offset:2432
	global_load_dwordx4 v[92:95], v18, s[12:13] offset:2496
	global_load_dwordx2 v[96:97], v[14:15], off offset:3328
	global_load_dwordx4 v[98:101], v18, s[12:13] offset:2560
	global_load_dwordx2 v[102:103], v[14:15], off offset:3360
	global_load_dwordx2 v[104:105], v[14:15], off offset:3392
	global_load_dwordx2 v[106:107], v[14:15], off offset:3424
	global_load_dwordx4 v[116:119], v18, s[12:13] offset:2624
	global_load_dwordx4 v[120:123], v18, s[12:13] offset:2688
	global_load_dwordx4 v[124:127], v18, s[12:13] offset:2752
	global_load_dwordx2 v[132:133], v[14:15], off offset:3456
	global_load_dwordx4 v[134:137], v18, s[12:13] offset:2816
	global_load_dwordx2 v[138:139], v[14:15], off offset:3488
	global_load_dwordx2 v[140:141], v[14:15], off offset:3520
	global_load_dwordx2 v[142:143], v[14:15], off offset:3552
	global_load_dwordx4 v[144:147], v18, s[12:13] offset:2880
	global_load_dwordx4 v[148:151], v18, s[12:13] offset:2944
	global_load_dwordx4 v[152:155], v18, s[12:13] offset:3008
	s_waitcnt lgkmcnt(0)
	v_add_f32_e32 v19, v110, v16
	ds_bpermute_b32 v28, v113, v19
	s_mov_b64 s[0:1], 0xdde0400
	v_lshl_add_u64 v[12:13], s[6:7], 0, v[12:13]
	v_lshl_add_u64 v[12:13], v[12:13], 0, s[0:1]
	s_mov_b32 s0, 0x800000
	s_waitcnt lgkmcnt(0)
	v_add_f32_e32 v19, v19, v28
	v_fmamk_f32 v19, v19, 0x3b800000, v180
	v_mul_f32_e32 v28, 0x4b800000, v19
	v_cmp_gt_f32_e32 vcc, s0, v19
	ds_read2_b64 v[4:7], v109 offset1:4
	v_cndmask_b32_e32 v19, v19, v28, vcc
	v_rsq_f32_e32 v19, v19
	v_lshl_add_u64 v[26:27], v[12:13], 0, v[2:3]
	s_waitcnt lgkmcnt(0)
	v_lshlrev_b32_e32 v29, 16, v4
	v_and_b32_e32 v31, 0xffff0000, v4
	v_mul_f32_e32 v4, 0x45800000, v19
	v_lshlrev_b32_e32 v33, 16, v5
	v_and_b32_e32 v35, 0xffff0000, v5
	v_cndmask_b32_e32 v5, v19, v4, vcc
	v_mov_b32_e32 v38, v5
	v_mov_b32_e32 v40, v5
	v_mov_b32_e32 v42, v5
	v_readlane_b32 s88, v243, 5
	v_readlane_b32 s20, v243, 30
	v_readlane_b32 s89, v243, 6
	v_readlane_b32 s0, v243, 8
	v_mov_b32_e32 v45, v3
	v_mov_b32_e32 v115, v3
	v_readlane_b32 s2, v244, 62
	v_readlane_b32 s10, v244, 2
	v_readlane_b32 s11, v244, 3
	v_mov_b32_e32 v51, v3
	v_readlane_b32 s9, v244, 1
	v_readlane_b32 s3, v244, 63
	v_readlane_b32 s14, v244, 6
	v_readlane_b32 s15, v244, 7
	v_readlane_b32 s5, v244, 58
	v_readlane_b32 s86, v243, 3
	v_readlane_b32 s22, v243, 28
	v_mov_b32_e32 v130, 0
	s_mov_b64 s[4:5], 0
	v_readlane_b32 s58, v243, 2
	v_readlane_b32 s87, v243, 4
	s_movk_i32 s84, 0x7f
	v_readlane_b32 s23, v243, 29
	v_readlane_b32 s21, v243, 31
	s_waitcnt vmcnt(31)
	v_lshlrev_b32_e32 v28, 16, v20
	v_mul_f32_e32 v4, 0xbfb8aa3b, v28
	v_exp_f32_e32 v4, v4
	v_and_b32_e32 v30, 0xffff0000, v20
	v_mul_f32_e32 v19, 0xbfb8aa3b, v30
	v_exp_f32_e32 v19, v19
	v_add_f32_e32 v4, 1.0, v4
	v_rcp_f32_e32 v4, v4
	v_lshlrev_b32_e32 v32, 16, v21
	v_and_b32_e32 v34, 0xffff0000, v21
	v_mul_f32_e32 v20, 0xbfb8aa3b, v32
	v_mul_f32_e32 v21, 0xbfb8aa3b, v34
	v_exp_f32_e32 v36, v20
	v_add_f32_e32 v19, 1.0, v19
	v_exp_f32_e32 v37, v21
	v_pk_mul_f32 v[20:21], v[4:5], v[28:29]
	v_rcp_f32_e32 v4, v19
	v_add_f32_e32 v19, 1.0, v36
	s_waitcnt vmcnt(30)
	v_mul_f32_e32 v8, v8, v21
	v_add_f32_e32 v36, 1.0, v37
	v_pk_mul_f32 v[28:29], v[4:5], v[30:31]
	v_rcp_f32_e32 v4, v19
	v_mul_f32_e32 v19, v20, v8
	v_mul_f32_e32 v8, v9, v29
	v_mul_f32_e32 v20, v28, v8
	v_pk_mul_f32 v[8:9], v[4:5], v[32:33]
	v_rcp_f32_e32 v4, v36
	v_mul_f32_e32 v9, v10, v9
	v_mul_f32_e32 v10, v8, v9
	v_cvt_pk_bf16_f32 v20, v19, v20
	v_pk_mul_f32 v[8:9], v[4:5], v[34:35]
	v_lshlrev_b32_e32 v28, 16, v7
	v_mul_f32_e32 v4, v11, v9
	v_mul_f32_e32 v4, v8, v4
	v_cvt_pk_bf16_f32 v21, v10, v4
	global_store_dwordx2 v[26:27], v[20:21], off
	v_and_b32_e32 v30, 0xffff0000, v7
	s_waitcnt vmcnt(30)
	v_lshlrev_b32_e32 v27, 16, v46
	v_and_b32_e32 v7, 0xffff0000, v46
	v_lshlrev_b32_e32 v29, 16, v47
	v_and_b32_e32 v31, 0xffff0000, v47
	v_mul_f32_e32 v4, 0xbfb8aa3b, v27
	v_mul_f32_e32 v19, 0xbfb8aa3b, v7
	v_mul_f32_e32 v22, 0xbfb8aa3b, v29
	v_mul_f32_e32 v23, 0xbfb8aa3b, v31
	v_exp_f32_e32 v4, v4
	v_exp_f32_e32 v19, v19
	v_exp_f32_e32 v22, v22
	v_exp_f32_e32 v23, v23
	v_add_f32_e32 v4, 1.0, v4
	v_add_f32_e32 v19, 1.0, v19
	v_add_f32_e32 v22, 1.0, v22
	v_add_f32_e32 v23, 1.0, v23
	v_rcp_f32_e32 v33, v4
	v_rcp_f32_e32 v35, v19
	v_rcp_f32_e32 v37, v22
	v_rcp_f32_e32 v39, v23
	v_lshlrev_b32_e32 v26, 16, v6
	v_and_b32_e32 v6, 0xffff0000, v6
	v_mov_b32_e32 v32, v5
	v_mov_b32_e32 v34, v5
	v_mov_b32_e32 v36, v5
	v_pk_mul_f32 v[22:23], v[32:33], v[26:27]
	v_pk_mul_f32 v[6:7], v[34:35], v[6:7]
	v_pk_mul_f32 v[26:27], v[36:37], v[28:29]
	v_mov_b32_e32 v21, v3
	v_or_b32_e32 v20, 32, v2
	v_pk_mul_f32 v[28:29], v[38:39], v[30:31]
	v_lshl_add_u64 v[20:21], v[12:13], 0, v[20:21]
	s_waitcnt vmcnt(29)
	v_and_b32_e32 v31, 0xffff0000, v53
	s_waitcnt vmcnt(27)
	v_mul_f32_e32 v4, v56, v22
	v_mul_f32_e32 v6, v57, v6
	v_mul_f32_e32 v8, v58, v26
	v_mul_f32_e32 v9, v59, v28
	v_mul_f32_e32 v6, v6, v7
	v_mul_f32_e32 v7, v8, v27
	v_mul_f32_e32 v4, v4, v23
	v_mul_f32_e32 v8, v9, v29
	v_cvt_pk_bf16_f32 v6, v4, v6
	v_cvt_pk_bf16_f32 v7, v7, v8
	global_store_dwordx2 v[20:21], v[6:7], off
	ds_read2_b64 v[20:23], v109 offset0:8 offset1:12
	v_lshlrev_b32_e32 v27, 16, v52
	v_lshlrev_b32_e32 v29, 16, v53
	v_mul_f32_e32 v4, 0xbfb8aa3b, v27
	v_mul_f32_e32 v25, 0xbfb8aa3b, v31
	s_waitcnt lgkmcnt(0)
	v_lshlrev_b32_e32 v28, 16, v21
	v_and_b32_e32 v30, 0xffff0000, v21
	v_and_b32_e32 v21, 0xffff0000, v52
	v_mul_f32_e32 v19, 0xbfb8aa3b, v21
	v_mul_f32_e32 v24, 0xbfb8aa3b, v29
	v_exp_f32_e32 v4, v4
	v_exp_f32_e32 v19, v19
	v_exp_f32_e32 v24, v24
	v_exp_f32_e32 v25, v25
	v_add_f32_e32 v4, 1.0, v4
	v_add_f32_e32 v19, 1.0, v19
	v_add_f32_e32 v24, 1.0, v24
	v_add_f32_e32 v25, 1.0, v25
	v_rcp_f32_e32 v33, v4
	v_rcp_f32_e32 v35, v19
	v_rcp_f32_e32 v37, v24
	v_rcp_f32_e32 v39, v25
	v_lshlrev_b32_e32 v26, 16, v20
	v_and_b32_e32 v20, 0xffff0000, v20
	v_pk_mul_f32 v[24:25], v[32:33], v[26:27]
	v_pk_mul_f32 v[20:21], v[34:35], v[20:21]
	v_pk_mul_f32 v[26:27], v[36:37], v[28:29]
	v_mov_b32_e32 v11, v3
	v_or_b32_e32 v10, 64, v2
	v_pk_mul_f32 v[28:29], v[38:39], v[30:31]
	v_lshl_add_u64 v[10:11], v[12:13], 0, v[10:11]
	v_mov_b32_e32 v30, v5
	s_waitcnt vmcnt(27)
	v_mul_f32_e32 v4, v60, v24
	v_mul_f32_e32 v6, v61, v20
	v_mul_f32_e32 v7, v62, v26
	v_mul_f32_e32 v8, v63, v28
	v_mul_f32_e32 v6, v6, v21
	v_mul_f32_e32 v7, v7, v27
	v_mul_f32_e32 v4, v4, v25
	v_mul_f32_e32 v8, v8, v29
	v_cvt_pk_bf16_f32 v6, v4, v6
	v_cvt_pk_bf16_f32 v7, v7, v8
	global_store_dwordx2 v[10:11], v[6:7], off
	v_lshlrev_b32_e32 v26, 16, v23
	v_and_b32_e32 v28, 0xffff0000, v23
	v_lshlrev_b32_e32 v21, 16, v54
	v_and_b32_e32 v23, 0xffff0000, v54
	v_lshlrev_b32_e32 v27, 16, v55
	v_and_b32_e32 v29, 0xffff0000, v55
	v_mul_f32_e32 v4, 0xbfb8aa3b, v21
	v_mul_f32_e32 v16, 0xbfb8aa3b, v23
	v_mul_f32_e32 v17, 0xbfb8aa3b, v27
	v_mul_f32_e32 v19, 0xbfb8aa3b, v29
	v_exp_f32_e32 v4, v4
	v_exp_f32_e32 v16, v16
	v_exp_f32_e32 v17, v17
	v_exp_f32_e32 v19, v19
	v_add_f32_e32 v4, 1.0, v4
	v_add_f32_e32 v16, 1.0, v16
	v_add_f32_e32 v17, 1.0, v17
	v_add_f32_e32 v19, 1.0, v19
	v_rcp_f32_e32 v31, v4
	v_rcp_f32_e32 v33, v16
	v_rcp_f32_e32 v35, v17
	v_rcp_f32_e32 v37, v19
	v_lshlrev_b32_e32 v20, 16, v22
	v_and_b32_e32 v22, 0xffff0000, v22
	v_pk_mul_f32 v[16:17], v[30:31], v[20:21]
	v_pk_mul_f32 v[20:21], v[32:33], v[22:23]
	v_pk_mul_f32 v[22:23], v[34:35], v[26:27]
	v_mov_b32_e32 v11, v3
	v_or_b32_e32 v10, 0x60, v2
	v_pk_mul_f32 v[26:27], v[36:37], v[28:29]
	v_lshl_add_u64 v[10:11], v[12:13], 0, v[10:11]
	s_waitcnt vmcnt(27)
	v_mul_f32_e32 v4, v64, v16
	v_mul_f32_e32 v6, v65, v20
	v_mul_f32_e32 v7, v66, v22
	v_mul_f32_e32 v8, v67, v26
	v_mul_f32_e32 v6, v6, v21
	v_mul_f32_e32 v7, v7, v23
	v_mul_f32_e32 v4, v4, v17
	v_mul_f32_e32 v8, v8, v27
	v_cvt_pk_bf16_f32 v6, v4, v6
	v_cvt_pk_bf16_f32 v7, v7, v8
	global_store_dwordx2 v[10:11], v[6:7], off
	ds_read2_b64 v[20:23], v109 offset0:16 offset1:20
	s_waitcnt vmcnt(27)
	v_lshlrev_b32_e32 v31, 16, v68
	v_lshlrev_b32_e32 v33, 16, v69
	v_and_b32_e32 v35, 0xffff0000, v69
	s_waitcnt lgkmcnt(0)
	v_lshlrev_b32_e32 v32, 16, v21
	v_and_b32_e32 v34, 0xffff0000, v21
	v_and_b32_e32 v21, 0xffff0000, v68
	v_mul_f32_e32 v4, 0xbfb8aa3b, v31
	v_mul_f32_e32 v19, 0xbfb8aa3b, v21
	v_mul_f32_e32 v24, 0xbfb8aa3b, v33
	v_mul_f32_e32 v25, 0xbfb8aa3b, v35
	v_exp_f32_e32 v4, v4
	v_exp_f32_e32 v19, v19
	v_exp_f32_e32 v24, v24
	v_exp_f32_e32 v25, v25
	v_add_f32_e32 v4, 1.0, v4
	v_add_f32_e32 v19, 1.0, v19
	v_add_f32_e32 v24, 1.0, v24
	v_add_f32_e32 v25, 1.0, v25
	v_rcp_f32_e32 v37, v4
	v_rcp_f32_e32 v39, v19
	v_rcp_f32_e32 v41, v24
	v_rcp_f32_e32 v43, v25
	v_lshlrev_b32_e32 v30, 16, v20
	v_and_b32_e32 v20, 0xffff0000, v20
	v_pk_mul_f32 v[24:25], v[36:37], v[30:31]
	v_pk_mul_f32 v[20:21], v[38:39], v[20:21]
	v_pk_mul_f32 v[30:31], v[40:41], v[32:33]
	v_mov_b32_e32 v17, v3
	v_or_b32_e32 v16, 0x80, v2
	v_pk_mul_f32 v[32:33], v[42:43], v[34:35]
	v_lshl_add_u64 v[16:17], v[12:13], 0, v[16:17]
	v_mov_b32_e32 v34, v5
	s_waitcnt vmcnt(26)
	v_mul_f32_e32 v4, v70, v24
	v_mul_f32_e32 v8, v71, v20
	v_mul_f32_e32 v9, v72, v30
	v_mul_f32_e32 v10, v73, v32
	v_mul_f32_e32 v8, v8, v21
	v_mul_f32_e32 v9, v9, v31
	v_mul_f32_e32 v4, v4, v25
	v_mul_f32_e32 v10, v10, v33
	v_cvt_pk_bf16_f32 v8, v4, v8
	v_cvt_pk_bf16_f32 v9, v9, v10
	global_store_dwordx2 v[16:17], v[8:9], off
	v_lshlrev_b32_e32 v24, 16, v23
	v_and_b32_e32 v30, 0xffff0000, v23
	s_waitcnt vmcnt(26)
	v_lshlrev_b32_e32 v21, 16, v74
	v_and_b32_e32 v23, 0xffff0000, v74
	v_lshlrev_b32_e32 v25, 16, v75
	v_and_b32_e32 v31, 0xffff0000, v75
	v_mul_f32_e32 v4, 0xbfb8aa3b, v21
	v_mul_f32_e32 v19, 0xbfb8aa3b, v23
	v_mul_f32_e32 v26, 0xbfb8aa3b, v25
	v_mul_f32_e32 v27, 0xbfb8aa3b, v31
	v_exp_f32_e32 v4, v4
	v_exp_f32_e32 v19, v19
	v_exp_f32_e32 v26, v26
	v_exp_f32_e32 v27, v27
	v_add_f32_e32 v4, 1.0, v4
	v_add_f32_e32 v19, 1.0, v19
	v_add_f32_e32 v26, 1.0, v26
	v_add_f32_e32 v27, 1.0, v27
	v_rcp_f32_e32 v33, v4
	v_rcp_f32_e32 v35, v19
	v_rcp_f32_e32 v37, v26
	v_rcp_f32_e32 v39, v27
	v_lshlrev_b32_e32 v20, 16, v22
	v_and_b32_e32 v22, 0xffff0000, v22
	v_mov_b32_e32 v32, v5
	v_pk_mul_f32 v[20:21], v[32:33], v[20:21]
	v_pk_mul_f32 v[22:23], v[34:35], v[22:23]
	v_pk_mul_f32 v[24:25], v[36:37], v[24:25]
	v_mov_b32_e32 v17, v3
	v_or_b32_e32 v16, 0xa0, v2
	v_pk_mul_f32 v[26:27], v[38:39], v[30:31]
	v_lshl_add_u64 v[16:17], v[12:13], 0, v[16:17]
	s_waitcnt vmcnt(25)
	v_and_b32_e32 v31, 0xffff0000, v77
	s_waitcnt vmcnt(23)
	v_mul_f32_e32 v4, v84, v20
	v_mul_f32_e32 v8, v85, v22
	v_mul_f32_e32 v9, v86, v24
	v_mul_f32_e32 v10, v87, v26
	v_mul_f32_e32 v8, v8, v23
	v_mul_f32_e32 v9, v9, v25
	v_mul_f32_e32 v4, v4, v21
	v_mul_f32_e32 v10, v10, v27
	v_cvt_pk_bf16_f32 v8, v4, v8
	v_cvt_pk_bf16_f32 v9, v9, v10
	global_store_dwordx2 v[16:17], v[8:9], off
	ds_read2_b64 v[20:23], v109 offset0:24 offset1:28
	v_lshlrev_b32_e32 v25, 16, v76
	v_lshlrev_b32_e32 v27, 16, v77
	v_mul_f32_e32 v4, 0xbfb8aa3b, v25
	v_mul_f32_e32 v29, 0xbfb8aa3b, v31
	s_waitcnt lgkmcnt(0)
	v_lshlrev_b32_e32 v26, 16, v21
	v_and_b32_e32 v30, 0xffff0000, v21
	v_and_b32_e32 v21, 0xffff0000, v76
	v_mul_f32_e32 v19, 0xbfb8aa3b, v21
	v_mul_f32_e32 v28, 0xbfb8aa3b, v27
	v_exp_f32_e32 v4, v4
	v_exp_f32_e32 v19, v19
	v_exp_f32_e32 v28, v28
	v_exp_f32_e32 v29, v29
	v_add_f32_e32 v4, 1.0, v4
	v_add_f32_e32 v19, 1.0, v19
	v_add_f32_e32 v28, 1.0, v28
	v_add_f32_e32 v29, 1.0, v29
	v_rcp_f32_e32 v33, v4
	v_rcp_f32_e32 v35, v19
	v_rcp_f32_e32 v37, v28
	v_rcp_f32_e32 v39, v29
	v_lshlrev_b32_e32 v24, 16, v20
	v_and_b32_e32 v20, 0xffff0000, v20
	v_pk_mul_f32 v[24:25], v[32:33], v[24:25]
	v_pk_mul_f32 v[20:21], v[34:35], v[20:21]
	v_pk_mul_f32 v[26:27], v[36:37], v[26:27]
	v_mov_b32_e32 v17, v3
	v_or_b32_e32 v16, 0xc0, v2
	v_pk_mul_f32 v[28:29], v[38:39], v[30:31]
	v_lshl_add_u64 v[16:17], v[12:13], 0, v[16:17]
	v_mov_b32_e32 v30, v5
	s_waitcnt vmcnt(23)
	v_mul_f32_e32 v4, v88, v24
	v_mul_f32_e32 v8, v89, v20
	v_mul_f32_e32 v9, v90, v26
	v_mul_f32_e32 v10, v91, v28
	v_mul_f32_e32 v8, v8, v21
	v_mul_f32_e32 v9, v9, v27
	v_mul_f32_e32 v4, v4, v25
	v_mul_f32_e32 v10, v10, v29
	v_cvt_pk_bf16_f32 v8, v4, v8
	v_cvt_pk_bf16_f32 v9, v9, v10
	global_store_dwordx2 v[16:17], v[8:9], off
	v_lshlrev_b32_e32 v26, 16, v23
	v_and_b32_e32 v28, 0xffff0000, v23
	v_lshlrev_b32_e32 v21, 16, v78
	v_and_b32_e32 v23, 0xffff0000, v78
	v_lshlrev_b32_e32 v27, 16, v79
	v_and_b32_e32 v29, 0xffff0000, v79
	v_mul_f32_e32 v4, 0xbfb8aa3b, v21
	v_mul_f32_e32 v6, 0xbfb8aa3b, v23
	v_mul_f32_e32 v7, 0xbfb8aa3b, v27
	v_mul_f32_e32 v19, 0xbfb8aa3b, v29
	v_exp_f32_e32 v4, v4
	v_exp_f32_e32 v6, v6
	v_exp_f32_e32 v7, v7
	v_exp_f32_e32 v19, v19
	v_add_f32_e32 v4, 1.0, v4
	v_add_f32_e32 v6, 1.0, v6
	v_add_f32_e32 v7, 1.0, v7
	v_add_f32_e32 v19, 1.0, v19
	v_rcp_f32_e32 v31, v4
	v_rcp_f32_e32 v33, v6
	v_rcp_f32_e32 v35, v7
	v_rcp_f32_e32 v37, v19
	v_lshlrev_b32_e32 v20, 16, v22
	v_and_b32_e32 v22, 0xffff0000, v22
	v_pk_mul_f32 v[6:7], v[30:31], v[20:21]
	v_pk_mul_f32 v[20:21], v[32:33], v[22:23]
	v_pk_mul_f32 v[22:23], v[34:35], v[26:27]
	v_mov_b32_e32 v17, v3
	v_or_b32_e32 v16, 0xe0, v2
	v_pk_mul_f32 v[26:27], v[36:37], v[28:29]
	v_lshl_add_u64 v[16:17], v[12:13], 0, v[16:17]
	s_waitcnt vmcnt(23)
	v_mul_f32_e32 v4, v92, v6
	v_mul_f32_e32 v6, v93, v20
	v_mul_f32_e32 v8, v94, v22
	v_mul_f32_e32 v9, v95, v26
	v_mul_f32_e32 v4, v4, v7
	v_mul_f32_e32 v6, v6, v21
	v_mul_f32_e32 v7, v8, v23
	v_mul_f32_e32 v8, v9, v27
	v_cvt_pk_bf16_f32 v6, v4, v6
	v_cvt_pk_bf16_f32 v7, v7, v8
	global_store_dwordx2 v[16:17], v[6:7], off
	ds_read2_b64 v[20:23], v109 offset0:32 offset1:36
	s_waitcnt vmcnt(23)
	v_lshlrev_b32_e32 v31, 16, v96
	v_lshlrev_b32_e32 v33, 16, v97
	v_and_b32_e32 v35, 0xffff0000, v97
	s_waitcnt lgkmcnt(0)
	v_lshlrev_b32_e32 v32, 16, v21
	v_and_b32_e32 v34, 0xffff0000, v21
	v_and_b32_e32 v21, 0xffff0000, v96
	v_mul_f32_e32 v4, 0xbfb8aa3b, v31
	v_mul_f32_e32 v19, 0xbfb8aa3b, v21
	v_mul_f32_e32 v24, 0xbfb8aa3b, v33
	v_mul_f32_e32 v25, 0xbfb8aa3b, v35
	v_exp_f32_e32 v4, v4
	v_exp_f32_e32 v19, v19
	v_exp_f32_e32 v24, v24
	v_exp_f32_e32 v25, v25
	v_add_f32_e32 v4, 1.0, v4
	v_add_f32_e32 v19, 1.0, v19
	v_add_f32_e32 v24, 1.0, v24
	v_add_f32_e32 v25, 1.0, v25
	v_rcp_f32_e32 v37, v4
	v_rcp_f32_e32 v39, v19
	v_rcp_f32_e32 v41, v24
	v_rcp_f32_e32 v43, v25
	v_lshlrev_b32_e32 v30, 16, v20
	v_and_b32_e32 v20, 0xffff0000, v20
	v_pk_mul_f32 v[24:25], v[36:37], v[30:31]
	v_pk_mul_f32 v[20:21], v[38:39], v[20:21]
	v_pk_mul_f32 v[30:31], v[40:41], v[32:33]
	v_mov_b32_e32 v17, v3
	v_or_b32_e32 v16, 0x100, v2
	v_pk_mul_f32 v[32:33], v[42:43], v[34:35]
	v_lshl_add_u64 v[16:17], v[12:13], 0, v[16:17]
	v_mov_b32_e32 v34, v5
	s_waitcnt vmcnt(22)
	v_mul_f32_e32 v4, v98, v24
	v_mul_f32_e32 v8, v99, v20
	v_mul_f32_e32 v9, v100, v30
	v_mul_f32_e32 v10, v101, v32
	v_mul_f32_e32 v8, v8, v21
	v_mul_f32_e32 v9, v9, v31
	v_mul_f32_e32 v4, v4, v25
	v_mul_f32_e32 v10, v10, v33
	v_cvt_pk_bf16_f32 v8, v4, v8
	v_cvt_pk_bf16_f32 v9, v9, v10
	global_store_dwordx2 v[16:17], v[8:9], off
	v_lshlrev_b32_e32 v24, 16, v23
	v_and_b32_e32 v30, 0xffff0000, v23
	s_waitcnt vmcnt(22)
	v_lshlrev_b32_e32 v21, 16, v102
	v_and_b32_e32 v23, 0xffff0000, v102
	v_lshlrev_b32_e32 v25, 16, v103
	v_and_b32_e32 v31, 0xffff0000, v103
	v_mul_f32_e32 v4, 0xbfb8aa3b, v21
	v_mul_f32_e32 v19, 0xbfb8aa3b, v23
	v_mul_f32_e32 v26, 0xbfb8aa3b, v25
	v_mul_f32_e32 v27, 0xbfb8aa3b, v31
	v_exp_f32_e32 v4, v4
	v_exp_f32_e32 v19, v19
	v_exp_f32_e32 v26, v26
	v_exp_f32_e32 v27, v27
	v_add_f32_e32 v4, 1.0, v4
	v_add_f32_e32 v19, 1.0, v19
	v_add_f32_e32 v26, 1.0, v26
	v_add_f32_e32 v27, 1.0, v27
	v_rcp_f32_e32 v33, v4
	v_rcp_f32_e32 v35, v19
	v_rcp_f32_e32 v37, v26
	v_rcp_f32_e32 v39, v27
	v_lshlrev_b32_e32 v20, 16, v22
	v_and_b32_e32 v22, 0xffff0000, v22
	v_mov_b32_e32 v32, v5
	v_pk_mul_f32 v[20:21], v[32:33], v[20:21]
	v_pk_mul_f32 v[22:23], v[34:35], v[22:23]
	v_pk_mul_f32 v[24:25], v[36:37], v[24:25]
	v_mov_b32_e32 v17, v3
	v_or_b32_e32 v16, 0x120, v2
	v_pk_mul_f32 v[26:27], v[38:39], v[30:31]
	v_lshl_add_u64 v[16:17], v[12:13], 0, v[16:17]
	s_waitcnt vmcnt(21)
	v_and_b32_e32 v31, 0xffff0000, v105
	s_waitcnt vmcnt(19)
	v_mul_f32_e32 v4, v116, v20
	v_mul_f32_e32 v8, v117, v22
	v_mul_f32_e32 v9, v118, v24
	v_mul_f32_e32 v10, v119, v26
	v_mul_f32_e32 v8, v8, v23
	v_mul_f32_e32 v9, v9, v25
	v_mul_f32_e32 v4, v4, v21
	v_mul_f32_e32 v10, v10, v27
	v_cvt_pk_bf16_f32 v8, v4, v8
	v_cvt_pk_bf16_f32 v9, v9, v10
	global_store_dwordx2 v[16:17], v[8:9], off
	ds_read2_b64 v[20:23], v109 offset0:40 offset1:44
	v_lshlrev_b32_e32 v25, 16, v104
	v_lshlrev_b32_e32 v27, 16, v105
	v_mul_f32_e32 v4, 0xbfb8aa3b, v25
	v_mul_f32_e32 v29, 0xbfb8aa3b, v31
	s_waitcnt lgkmcnt(0)
	v_lshlrev_b32_e32 v26, 16, v21
	v_and_b32_e32 v30, 0xffff0000, v21
	v_and_b32_e32 v21, 0xffff0000, v104
	v_mul_f32_e32 v19, 0xbfb8aa3b, v21
	v_mul_f32_e32 v28, 0xbfb8aa3b, v27
	v_exp_f32_e32 v4, v4
	v_exp_f32_e32 v19, v19
	v_exp_f32_e32 v28, v28
	v_exp_f32_e32 v29, v29
	v_add_f32_e32 v4, 1.0, v4
	v_add_f32_e32 v19, 1.0, v19
	v_add_f32_e32 v28, 1.0, v28
	v_add_f32_e32 v29, 1.0, v29
	v_rcp_f32_e32 v33, v4
	v_rcp_f32_e32 v35, v19
	v_rcp_f32_e32 v37, v28
	v_rcp_f32_e32 v39, v29
	v_lshlrev_b32_e32 v24, 16, v20
	v_and_b32_e32 v20, 0xffff0000, v20
	v_pk_mul_f32 v[24:25], v[32:33], v[24:25]
	v_pk_mul_f32 v[20:21], v[34:35], v[20:21]
	v_pk_mul_f32 v[26:27], v[36:37], v[26:27]
	v_mov_b32_e32 v17, v3
	v_or_b32_e32 v16, 0x140, v2
	v_pk_mul_f32 v[28:29], v[38:39], v[30:31]
	v_lshl_add_u64 v[16:17], v[12:13], 0, v[16:17]
	v_mov_b32_e32 v30, v5
	s_waitcnt vmcnt(19)
	v_mul_f32_e32 v4, v120, v24
	v_mul_f32_e32 v8, v121, v20
	v_mul_f32_e32 v9, v122, v26
	v_mul_f32_e32 v10, v123, v28
	v_mul_f32_e32 v8, v8, v21
	v_mul_f32_e32 v9, v9, v27
	v_mul_f32_e32 v4, v4, v25
	v_mul_f32_e32 v10, v10, v29
	v_cvt_pk_bf16_f32 v8, v4, v8
	v_cvt_pk_bf16_f32 v9, v9, v10
	global_store_dwordx2 v[16:17], v[8:9], off
	v_lshlrev_b32_e32 v26, 16, v23
	v_and_b32_e32 v28, 0xffff0000, v23
	v_lshlrev_b32_e32 v21, 16, v106
	v_and_b32_e32 v23, 0xffff0000, v106
	v_lshlrev_b32_e32 v27, 16, v107
	v_and_b32_e32 v29, 0xffff0000, v107
	v_mul_f32_e32 v4, 0xbfb8aa3b, v21
	v_mul_f32_e32 v6, 0xbfb8aa3b, v23
	v_mul_f32_e32 v7, 0xbfb8aa3b, v27
	v_mul_f32_e32 v19, 0xbfb8aa3b, v29
	v_exp_f32_e32 v4, v4
	v_exp_f32_e32 v6, v6
	v_exp_f32_e32 v7, v7
	v_exp_f32_e32 v19, v19
	v_add_f32_e32 v4, 1.0, v4
	v_add_f32_e32 v6, 1.0, v6
	v_add_f32_e32 v7, 1.0, v7
	v_add_f32_e32 v19, 1.0, v19
	v_rcp_f32_e32 v31, v4
	v_rcp_f32_e32 v33, v6
	v_rcp_f32_e32 v35, v7
	v_rcp_f32_e32 v37, v19
	v_lshlrev_b32_e32 v20, 16, v22
	v_and_b32_e32 v22, 0xffff0000, v22
	v_pk_mul_f32 v[6:7], v[30:31], v[20:21]
	v_pk_mul_f32 v[20:21], v[32:33], v[22:23]
	v_pk_mul_f32 v[22:23], v[34:35], v[26:27]
	v_mov_b32_e32 v17, v3
	v_or_b32_e32 v16, 0x160, v2
	v_pk_mul_f32 v[26:27], v[36:37], v[28:29]
	v_lshl_add_u64 v[16:17], v[12:13], 0, v[16:17]
	s_waitcnt vmcnt(19)
	v_mul_f32_e32 v4, v124, v6
	v_mul_f32_e32 v6, v125, v20
	v_mul_f32_e32 v8, v126, v22
	v_mul_f32_e32 v9, v127, v26
	v_mul_f32_e32 v4, v4, v7
	v_mul_f32_e32 v6, v6, v21
	v_mul_f32_e32 v7, v8, v23
	v_mul_f32_e32 v8, v9, v27
	v_cvt_pk_bf16_f32 v6, v4, v6
	v_cvt_pk_bf16_f32 v7, v7, v8
	global_store_dwordx2 v[16:17], v[6:7], off
	ds_read2_b64 v[20:23], v109 offset0:48 offset1:52
	v_mov_b32_e32 v17, v3
	v_or_b32_e32 v16, 0x180, v2
	v_lshl_add_u64 v[14:15], v[12:13], 0, v[16:17]
	s_waitcnt lgkmcnt(0)
	v_lshlrev_b32_e32 v30, 16, v21
	v_and_b32_e32 v32, 0xffff0000, v21
	s_waitcnt vmcnt(19)
	v_lshlrev_b32_e32 v17, 16, v132
	v_and_b32_e32 v21, 0xffff0000, v132
	v_lshlrev_b32_e32 v31, 16, v133
	v_and_b32_e32 v33, 0xffff0000, v133
	v_mul_f32_e32 v4, 0xbfb8aa3b, v17
	v_mul_f32_e32 v19, 0xbfb8aa3b, v21
	v_mul_f32_e32 v24, 0xbfb8aa3b, v31
	v_mul_f32_e32 v25, 0xbfb8aa3b, v33
	v_exp_f32_e32 v4, v4
	v_exp_f32_e32 v19, v19
	v_exp_f32_e32 v24, v24
	v_exp_f32_e32 v25, v25
	v_add_f32_e32 v4, 1.0, v4
	v_add_f32_e32 v19, 1.0, v19
	v_add_f32_e32 v24, 1.0, v24
	v_add_f32_e32 v25, 1.0, v25
	v_rcp_f32_e32 v35, v4
	v_rcp_f32_e32 v37, v19
	v_rcp_f32_e32 v39, v24
	v_rcp_f32_e32 v41, v25
	v_lshlrev_b32_e32 v16, 16, v20
	v_and_b32_e32 v20, 0xffff0000, v20
	v_pk_mul_f32 v[16:17], v[34:35], v[16:17]
	v_pk_mul_f32 v[20:21], v[36:37], v[20:21]
	v_pk_mul_f32 v[24:25], v[38:39], v[30:31]
	v_pk_mul_f32 v[30:31], v[40:41], v[32:33]
	v_mov_b32_e32 v32, v5
	s_waitcnt vmcnt(18)
	v_mul_f32_e32 v4, v134, v16
	v_mul_f32_e32 v8, v135, v20
	v_mul_f32_e32 v9, v136, v24
	v_mul_f32_e32 v10, v137, v30
	v_mul_f32_e32 v8, v8, v21
	v_mul_f32_e32 v9, v9, v25
	v_mul_f32_e32 v4, v4, v17
	v_mul_f32_e32 v10, v10, v31
	v_cvt_pk_bf16_f32 v8, v4, v8
	v_cvt_pk_bf16_f32 v9, v9, v10
	global_store_dwordx2 v[14:15], v[8:9], off
	v_lshlrev_b32_e32 v16, 16, v22
	v_and_b32_e32 v20, 0xffff0000, v22
	v_lshlrev_b32_e32 v22, 16, v23
	v_and_b32_e32 v24, 0xffff0000, v23
	s_waitcnt vmcnt(18)
	v_lshlrev_b32_e32 v17, 16, v138
	v_and_b32_e32 v21, 0xffff0000, v138
	v_lshlrev_b32_e32 v23, 16, v139
	v_and_b32_e32 v25, 0xffff0000, v139
	v_mul_f32_e32 v4, 0xbfb8aa3b, v17
	v_mul_f32_e32 v19, 0xbfb8aa3b, v21
	v_mul_f32_e32 v26, 0xbfb8aa3b, v23
	v_mul_f32_e32 v27, 0xbfb8aa3b, v25
	v_exp_f32_e32 v4, v4
	v_exp_f32_e32 v19, v19
	v_exp_f32_e32 v26, v26
	v_exp_f32_e32 v27, v27
	v_add_f32_e32 v4, 1.0, v4
	v_add_f32_e32 v19, 1.0, v19
	v_add_f32_e32 v26, 1.0, v26
	v_add_f32_e32 v27, 1.0, v27
	v_rcp_f32_e32 v31, v4
	v_rcp_f32_e32 v33, v19
	v_rcp_f32_e32 v35, v26
	v_rcp_f32_e32 v37, v27
	v_mov_b32_e32 v30, v5
	v_pk_mul_f32 v[16:17], v[30:31], v[16:17]
	v_pk_mul_f32 v[20:21], v[32:33], v[20:21]
	v_pk_mul_f32 v[22:23], v[34:35], v[22:23]
	v_mov_b32_e32 v15, v3
	v_or_b32_e32 v14, 0x1a0, v2
	v_pk_mul_f32 v[24:25], v[36:37], v[24:25]
	v_lshl_add_u64 v[14:15], v[12:13], 0, v[14:15]
	s_waitcnt vmcnt(17)
	v_and_b32_e32 v27, 0xffff0000, v141
	s_waitcnt vmcnt(15)
	v_mul_f32_e32 v4, v144, v16
	v_mul_f32_e32 v8, v145, v20
	v_mul_f32_e32 v9, v146, v22
	v_mul_f32_e32 v10, v147, v24
	v_mul_f32_e32 v8, v8, v21
	v_mul_f32_e32 v9, v9, v23
	v_mul_f32_e32 v4, v4, v17
	v_mul_f32_e32 v10, v10, v25
	v_cvt_pk_bf16_f32 v8, v4, v8
	v_cvt_pk_bf16_f32 v9, v9, v10
	global_store_dwordx2 v[14:15], v[8:9], off
	ds_read2_b64 v[14:17], v109 offset0:56 offset1:60
	v_lshlrev_b32_e32 v23, 16, v140
	v_lshlrev_b32_e32 v25, 16, v141
	v_mul_f32_e32 v4, 0xbfb8aa3b, v23
	v_mul_f32_e32 v29, 0xbfb8aa3b, v27
	s_waitcnt lgkmcnt(0)
	v_lshlrev_b32_e32 v24, 16, v15
	v_and_b32_e32 v26, 0xffff0000, v15
	v_and_b32_e32 v15, 0xffff0000, v140
	v_mul_f32_e32 v19, 0xbfb8aa3b, v15
	v_mul_f32_e32 v28, 0xbfb8aa3b, v25
	v_exp_f32_e32 v4, v4
	v_exp_f32_e32 v19, v19
	v_exp_f32_e32 v28, v28
	v_exp_f32_e32 v29, v29
	v_add_f32_e32 v4, 1.0, v4
	v_add_f32_e32 v19, 1.0, v19
	v_add_f32_e32 v28, 1.0, v28
	v_add_f32_e32 v29, 1.0, v29
	v_rcp_f32_e32 v31, v4
	v_rcp_f32_e32 v33, v19
	v_rcp_f32_e32 v35, v28
	v_rcp_f32_e32 v37, v29
	v_lshlrev_b32_e32 v22, 16, v14
	v_and_b32_e32 v14, 0xffff0000, v14
	v_pk_mul_f32 v[22:23], v[30:31], v[22:23]
	v_pk_mul_f32 v[14:15], v[32:33], v[14:15]
	v_pk_mul_f32 v[24:25], v[34:35], v[24:25]
	v_mov_b32_e32 v21, v3
	v_or_b32_e32 v20, 0x1c0, v2
	v_pk_mul_f32 v[26:27], v[36:37], v[26:27]
	v_lshl_add_u64 v[20:21], v[12:13], 0, v[20:21]
	v_or_b32_e32 v2, 0x1e0, v2
	v_mov_b32_e32 v28, v5
	v_lshlrev_b32_e32 v19, 16, v143
	v_lshl_add_u64 v[12:13], v[12:13], 0, v[2:3]
	v_mov_b32_e32 v30, v0
	s_waitcnt vmcnt(15)
	v_mul_f32_e32 v4, v148, v22
	v_mul_f32_e32 v8, v149, v14
	v_mul_f32_e32 v9, v150, v24
	v_mul_f32_e32 v10, v151, v26
	v_mul_f32_e32 v8, v8, v15
	v_mul_f32_e32 v9, v9, v25
	v_mul_f32_e32 v4, v4, v23
	v_mul_f32_e32 v10, v10, v27
	v_cvt_pk_bf16_f32 v8, v4, v8
	v_cvt_pk_bf16_f32 v9, v9, v10
	global_store_dwordx2 v[20:21], v[8:9], off
	v_lshlrev_b32_e32 v18, 16, v17
	v_and_b32_e32 v20, 0xffff0000, v17
	v_mov_b32_e32 v22, v5
	v_mov_b32_e32 v24, v5
	v_mov_b32_e32 v26, v5
	v_lshlrev_b32_e32 v5, 16, v142
	v_and_b32_e32 v17, 0xffff0000, v142
	v_and_b32_e32 v21, 0xffff0000, v143
	v_mul_f32_e32 v2, 0xbfb8aa3b, v5
	v_mul_f32_e32 v6, 0xbfb8aa3b, v17
	v_mul_f32_e32 v7, 0xbfb8aa3b, v19
	v_mul_f32_e32 v23, 0xbfb8aa3b, v21
	v_exp_f32_e32 v2, v2
	v_exp_f32_e32 v6, v6
	v_exp_f32_e32 v7, v7
	v_exp_f32_e32 v23, v23
	v_add_f32_e32 v2, 1.0, v2
	v_add_f32_e32 v6, 1.0, v6
	v_add_f32_e32 v7, 1.0, v7
	v_add_f32_e32 v29, 1.0, v23
	v_rcp_f32_e32 v23, v2
	v_rcp_f32_e32 v25, v6
	v_rcp_f32_e32 v27, v7
	v_rcp_f32_e32 v29, v29
	v_lshlrev_b32_e32 v4, 16, v16
	v_and_b32_e32 v16, 0xffff0000, v16
	v_pk_mul_f32 v[4:5], v[22:23], v[4:5]
	v_pk_mul_f32 v[6:7], v[24:25], v[16:17]
	v_pk_mul_f32 v[16:17], v[26:27], v[18:19]
	v_pk_mul_f32 v[18:19], v[28:29], v[20:21]
	v_mov_b64_e32 v[14:15], s[88:89]
	s_waitcnt vmcnt(15)
	v_mul_f32_e32 v2, v152, v4
	v_mul_f32_e32 v4, v153, v6
	v_mul_f32_e32 v6, v154, v16
	v_mul_f32_e32 v8, v155, v18
	v_mul_f32_e32 v2, v2, v5
	v_mul_f32_e32 v4, v4, v7
	v_mul_f32_e32 v5, v6, v17
	v_mul_f32_e32 v6, v8, v19
	v_cvt_pk_bf16_f32 v4, v2, v4
	v_cvt_pk_bf16_f32 v5, v5, v6
	global_store_dwordx2 v[12:13], v[4:5], off
	s_nop 0
	v_and_b32_e32 v52, 15, v30
	v_ashrrev_i32_e32 v2, 6, v30
	v_or_b32_e32 v5, s20, v52
	v_ashrrev_i32_e32 v46, 1, v30
	v_lshl_add_u32 v116, v2, 4, v5
	v_lshl_add_u32 v4, s0, 8, v46
	v_mad_i64_i32 v[118:119], s[0:1], v116, s92, v[14:15]
	v_ashrrev_i32_e32 v5, 31, v4
	v_readlane_b32 s0, v244, 50
	v_and_b32_e32 v50, 1, v30
	v_lshlrev_b64 v[4:5], 10, v[4:5]
	v_readlane_b32 s1, v244, 51
	v_bfe_u32 v47, v30, 4, 2
	v_lshlrev_b32_e32 v44, 6, v50
	v_lshl_add_u64 v[4:5], s[0:1], 0, v[4:5]
	v_lshlrev_b32_e32 v114, 4, v47
	v_lshl_add_u64 v[20:21], v[4:5], 0, v[44:45]
	v_lshl_add_u64 v[120:121], v[118:119], 0, v[114:115]
	global_load_dwordx4 v[4:7], v[20:21], off offset:48
	global_load_dwordx4 v[12:15], v[20:21], off offset:32
	global_load_dwordx4 v[16:19], v[20:21], off offset:16
	global_load_dwordx4 v[8:11], v[20:21], off
	global_load_dwordx4 v[28:31], v[20:21], off offset:512
	global_load_dwordx4 v[32:35], v[20:21], off offset:528
	global_load_dwordx4 v[36:39], v[20:21], off offset:544
	global_load_dwordx4 v[40:43], v[20:21], off offset:560
	s_nop 0
	global_load_dwordx4 v[20:23], v[120:121], off offset:3584
	global_load_dwordx4 v[24:27], v[120:121], off offset:3648
	v_readlane_b32 s0, v243, 0
	v_mul_lo_u32 v45, v46, s97
	s_and_b32 s0, s0, 7
	v_add_u32_e32 v48, 0, v45
	s_lshl_b32 s2, s0, 18
	v_add_u32_e32 v132, v48, v44
	v_mad_u64_u32 v[48:49], s[0:1], v46, s98, v[48:49]
	v_mul_u32_u24_e32 v45, 0x4200, v50
	v_lshlrev_b32_e32 v50, 7, v50
	v_mul_lo_u32 v131, v2, s93
	v_lshlrev_b32_e32 v2, 3, v47
	v_lshl_add_u64 v[122:123], s[10:11], 0, v[50:51]
	v_lshlrev_b32_e32 v50, 5, v47
	v_or_b32_e32 v47, 16, v52
	s_movk_i32 s0, 0x210
	v_lshl_add_u64 v[124:125], s[8:9], 0, v[50:51]
	global_load_dwordx4 v[224:227], v[124:125], off
	global_load_dwordx4 v[228:231], v[124:125], off offset:128
	global_load_dwordx4 v[232:235], v[124:125], off offset:16
	global_load_dwordx4 v[236:239], v[124:125], off offset:144
	v_mul_u32_u24_e32 v51, 0x210, v47
	v_mad_u32_u24 v47, v52, s0, v131
	v_add3_u32 v134, v47, v2, s96
	v_ashrrev_i32_e32 v47, 31, v46
	v_lshlrev_b64 v[46:47], 10, v[46:47]
	v_add_u32_e32 v49, 0, v114
	s_mov_b32 s1, s3
	v_lshl_add_u64 v[46:47], s[2:3], 0, v[46:47]
	v_mov_b32_e32 v133, v49
	v_mul_u32_u24_e32 v50, 0x90, v52
	v_writelane_b32 v244, s0, 62
	v_or_b32_e32 v46, v46, v44
	v_mul_u32_u24_e32 v115, 0x210, v52
	v_ashrrev_i32_e32 v117, 31, v116
	v_writelane_b32 v244, s1, 63
	v_lshl_add_u64 v[126:127], s[6:7], 0, v[46:47]
	s_mov_b64 s[0:1], 64
	v_and_b32_e32 v241, 24, v48
	v_and_b32_e32 v242, 32, v48
	v_and_b32_e32 v48, 0xffffffc7, v48
	v_lshlrev_b32_e32 v241, 1, v241
	v_lshrrev_b32_e32 v242, 2, v242
	v_or3_b32 v48, v48, v241, v242
	v_add_u32_e32 v135, v48, v45
	v_add_u32_e32 v136, v49, v50
	v_add_u32_e32 v137, v133, v51
	v_add_u32_e32 v240, v133, v115
	v_add_u32_e32 v240, 0x9000, v240
	v_add_u32_e32 v241, 0x9000, v137
	v_add_u32_e32 v242, 0xb000, v137
	v_add_u32_e32 v245, 0xd000, v137
	s_branch .LBB0_210
.LBB0_209:
	ds_read_b128 v[172:175], v136
	ds_read_b128 v[176:179], v136 offset:64
	ds_read_b128 v[196:199], v136 offset:2304
	ds_read_b128 v[200:203], v136 offset:2368
	ds_read_b128 v[204:207], v136 offset:4672
	ds_read_b128 v[208:211], v136 offset:4608
	ds_read_b128 v[212:215], v136 offset:6912
	ds_read_b128 v[216:219], v136 offset:6976
	s_add_u32 s0, s0, 64
	s_addc_u32 s1, s1, 0
	s_waitcnt lgkmcnt(7)
	v_mfma_f32_16x16x32_bf16 v[48:51], v[172:175], v[104:107], 0
	ds_read_b128 v[220:223], v136 offset:9216
	s_add_u32 s4, s4, 0x80
	s_addc_u32 s5, s5, 0
	s_cmpk_lg_i32 s4, 0x200
	s_waitcnt lgkmcnt(6)
	v_mfma_f32_16x16x32_bf16 v[56:59], v[196:199], v[104:107], 0
	ds_read_b128 v[172:175], v136 offset:11520
	v_mfma_f32_16x16x32_bf16 v[108:111], v[176:179], v[44:47], v[48:51]
	ds_read_b128 v[196:199], v136 offset:9280
	s_nop 1
	s_waitcnt lgkmcnt(7)
	v_mfma_f32_16x16x32_bf16 v[100:103], v[200:203], v[44:47], v[56:59]
	ds_read_b128 v[176:179], v136 offset:11584
	s_nop 2
	s_waitcnt lgkmcnt(6)
	v_mfma_f32_16x16x32_bf16 v[48:51], v[208:211], v[104:107], 0
	ds_read_b128 v[200:203], v136 offset:13888
	v_mfma_f32_16x16x32_bf16 v[96:99], v[204:207], v[44:47], v[48:51]
	ds_read_b128 v[208:211], v136 offset:13824
	s_nop 6
	s_waitcnt lgkmcnt(7)
	v_mfma_f32_16x16x32_bf16 v[52:55], v[212:215], v[104:107], 0
	ds_read_b128 v[204:207], v136 offset:16128
	s_waitcnt lgkmcnt(7)
	v_mfma_f32_16x16x32_bf16 v[92:95], v[216:219], v[44:47], v[52:55]
	ds_read_b128 v[212:215], v136 offset:16192
	s_waitcnt lgkmcnt(7)
	v_mfma_f32_16x16x32_bf16 v[52:55], v[220:223], v[104:107], 0
	ds_read_b128 v[216:219], v136 offset:18432
	s_waitcnt lgkmcnt(6)
	v_mfma_f32_16x16x32_bf16 v[88:91], v[196:199], v[44:47], v[52:55]
	ds_read_b128 v[220:223], v136 offset:18496
	s_nop 0
	v_mfma_f32_16x16x32_bf16 v[52:55], v[172:175], v[104:107], 0
	ds_read_b128 v[196:199], v136 offset:20736
	s_waitcnt lgkmcnt(7)
	v_mfma_f32_16x16x32_bf16 v[84:87], v[176:179], v[44:47], v[52:55]
	ds_read_b128 v[172:175], v136 offset:20800
	s_waitcnt lgkmcnt(6)
	v_mfma_f32_16x16x32_bf16 v[52:55], v[208:211], v[104:107], 0
	ds_read_b128 v[176:179], v136 offset:23040
	v_mfma_f32_16x16x32_bf16 v[80:83], v[200:203], v[44:47], v[52:55]
	ds_read_b128 v[208:211], v136 offset:23104
	s_waitcnt lgkmcnt(7)
	s_nop 0
	v_mfma_f32_16x16x32_bf16 v[52:55], v[204:207], v[104:107], 0
	ds_read_b128 v[200:203], v136 offset:25344
	s_waitcnt lgkmcnt(7)
	v_mfma_f32_16x16x32_bf16 v[76:79], v[212:215], v[44:47], v[52:55]
	ds_read_b128 v[204:207], v136 offset:25408
	s_waitcnt lgkmcnt(7)
	v_mfma_f32_16x16x32_bf16 v[52:55], v[216:219], v[104:107], 0
	ds_read_b128 v[212:215], v136 offset:27648
	s_waitcnt lgkmcnt(7)
	v_mfma_f32_16x16x32_bf16 v[68:71], v[220:223], v[44:47], v[52:55]
	ds_read_b128 v[216:219], v136 offset:27712
	s_waitcnt lgkmcnt(7)
	v_mfma_f32_16x16x32_bf16 v[52:55], v[196:199], v[104:107], 0
	ds_read_b128 v[220:223], v136 offset:29952
	s_waitcnt lgkmcnt(6)
	v_mfma_f32_16x16x32_bf16 v[56:59], v[176:179], v[104:107], 0
	ds_read_b128 v[196:199], v136 offset:32256
	s_waitcnt lgkmcnt(6)
	v_mfma_f32_16x16x32_bf16 v[72:75], v[208:211], v[44:47], v[56:59]
	ds_read_b128 v[176:179], v136 offset:32320
	v_mfma_f32_16x16x32_bf16 v[64:67], v[172:175], v[44:47], v[52:55]
	ds_read_b128 v[208:211], v136 offset:30016
	s_nop 4
	v_max3_f32 v56, v108, s16, v109
	v_max3_f32 v56, v56, v110, v111
	v_max3_f32 v60, v56, v100, v101
	s_waitcnt lgkmcnt(7)
	v_mfma_f32_16x16x32_bf16 v[56:59], v[200:203], v[104:107], 0
	ds_read_b128 v[172:175], v136 offset:34560
	v_max3_f32 v60, v60, v102, v103
	v_max3_f32 v60, v60, v96, v97
	v_max3_f32 v138, v60, v98, v99
	s_waitcnt lgkmcnt(7)
	v_mfma_f32_16x16x32_bf16 v[60:63], v[204:207], v[44:47], v[56:59]
	ds_read_b128 v[200:203], v136 offset:34624
	v_max3_f32 v56, v138, v92, v93
	v_max3_f32 v56, v56, v94, v95
	v_max3_f32 v56, v56, v88, v89
	s_waitcnt lgkmcnt(7)
	v_mfma_f32_16x16x32_bf16 v[48:51], v[212:215], v[104:107], 0
	ds_read_b128 v[204:207], v240
	v_max3_f32 v56, v56, v90, v91
	v_max3_f32 v56, v56, v84, v85
	v_max3_f32 v138, v56, v86, v87
	s_waitcnt lgkmcnt(7)
	v_mfma_f32_16x16x32_bf16 v[56:59], v[216:219], v[44:47], v[48:51]
	ds_read_b128 v[212:215], v241
	s_nop 2
	v_max3_f32 v48, v138, v80, v81
	v_max3_f32 v48, v48, v82, v83
	v_max3_f32 v52, v48, v76, v77
	s_waitcnt lgkmcnt(7)
	v_mfma_f32_16x16x32_bf16 v[48:51], v[220:223], v[104:107], 0
	ds_read_b128 v[216:219], v242 offset:256
	v_max3_f32 v52, v52, v78, v79
	v_max3_f32 v52, v52, v68, v69
	v_max3_f32 v138, v52, v70, v71
	s_waitcnt lgkmcnt(5)
	v_mfma_f32_16x16x32_bf16 v[52:55], v[208:211], v[44:47], v[48:51]
	ds_read_b128 v[220:223], v245 offset:512
	s_nop 2
	v_max3_f32 v48, v138, v64, v65
	v_max3_f32 v48, v48, v66, v67
	v_max3_f32 v138, v48, v72, v73
	s_nop 0
	v_mfma_f32_16x16x32_bf16 v[48:51], v[196:199], v[104:107], 0
	ds_read_b128 v[208:211], v240 offset:64
	v_max3_f32 v138, v138, v74, v75
	v_max3_f32 v138, v138, v60, v61
	v_max3_f32 v138, v138, v62, v63
	s_waitcnt lgkmcnt(6)
	v_mfma_f32_16x16x32_bf16 v[104:107], v[172:175], v[104:107], 0
	ds_read_b128 v[196:199], v241 offset:64
	v_max3_f32 v138, v138, v56, v57
	v_max3_f32 v138, v138, v58, v59
	v_max3_f32 v138, v138, v52, v53
	v_mfma_f32_16x16x32_bf16 v[48:51], v[176:179], v[44:47], v[48:51]
	ds_read_b128 v[172:175], v242 offset:320
	v_max3_f32 v138, v138, v54, v55
	s_waitcnt lgkmcnt(7)
	v_mfma_f32_16x16x32_bf16 v[44:47], v[200:203], v[44:47], v[104:107]
	ds_read_b128 v[176:179], v245 offset:576
	s_nop 4
	v_max3_f32 v138, v138, v48, v49
	v_max3_f32 v138, v138, v50, v51
	s_nop 0
	v_max3_f32 v104, v138, v44, v45
	v_max3_f32 v104, v104, v46, v47
	ds_bpermute_b32 v105, v128, v104
	s_waitcnt lgkmcnt(0)
	v_max_f32_e32 v105, v105, v105
	v_max_f32_e32 v104, v104, v105
	ds_bpermute_b32 v105, v113, v104
	s_waitcnt lgkmcnt(0)
	v_max_f32_e32 v105, v105, v105
	v_max_f32_e32 v104, v104, v105
	v_sub_f32_e32 v105, v108, v104
	v_exp_f32_e32 v106, v105
	v_sub_f32_e32 v105, v109, v104
	v_exp_f32_e32 v107, v105
	v_sub_f32_e32 v105, v110, v104
	v_exp_f32_e32 v108, v105
	v_sub_f32_e32 v105, v111, v104
	v_exp_f32_e32 v110, v105
	v_sub_f32_e32 v100, v100, v104
	v_add_f32_e32 v105, 0, v106
	v_exp_f32_e32 v109, v100
	v_sub_f32_e32 v100, v101, v104
	v_add_f32_e32 v105, v107, v105
	v_exp_f32_e32 v111, v100
	v_sub_f32_e32 v100, v102, v104
	v_add_f32_e32 v105, v108, v105
	v_exp_f32_e32 v138, v100
	v_sub_f32_e32 v100, v103, v104
	v_add_f32_e32 v105, v110, v105
	v_exp_f32_e32 v139, v100
	v_add_f32_e32 v100, v109, v105
	v_add_f32_e32 v100, v111, v100
	v_add_f32_e32 v100, v138, v100
	v_sub_f32_e32 v96, v96, v104
	v_add_f32_e32 v102, v139, v100
	v_exp_f32_e32 v100, v96
	v_sub_f32_e32 v96, v97, v104
	v_exp_f32_e32 v101, v96
	v_sub_f32_e32 v96, v98, v104
	v_exp_f32_e32 v97, v96
	v_sub_f32_e32 v96, v99, v104
	v_exp_f32_e32 v98, v96
	v_sub_f32_e32 v92, v92, v104
	v_add_f32_e32 v96, v100, v102
	v_exp_f32_e32 v99, v92
	v_sub_f32_e32 v92, v93, v104
	v_add_f32_e32 v96, v101, v96
	v_exp_f32_e32 v102, v92
	v_sub_f32_e32 v92, v94, v104
	v_add_f32_e32 v96, v97, v96
	v_exp_f32_e32 v103, v92
	v_sub_f32_e32 v92, v95, v104
	v_add_f32_e32 v96, v98, v96
	v_exp_f32_e32 v105, v92
	v_add_f32_e32 v92, v99, v96
	v_add_f32_e32 v92, v102, v92
	v_add_f32_e32 v92, v103, v92
	v_sub_f32_e32 v88, v88, v104
	v_add_f32_e32 v94, v105, v92
	v_exp_f32_e32 v92, v88
	v_sub_f32_e32 v88, v89, v104
	v_exp_f32_e32 v93, v88
	v_sub_f32_e32 v88, v90, v104
	v_exp_f32_e32 v89, v88
	v_sub_f32_e32 v88, v91, v104
	v_exp_f32_e32 v90, v88
	v_sub_f32_e32 v84, v84, v104
	v_add_f32_e32 v88, v92, v94
	v_exp_f32_e32 v91, v84
	v_sub_f32_e32 v84, v85, v104
	v_add_f32_e32 v88, v93, v88
	v_exp_f32_e32 v94, v84
	v_sub_f32_e32 v84, v86, v104
	v_add_f32_e32 v88, v89, v88
	v_exp_f32_e32 v95, v84
	v_sub_f32_e32 v84, v87, v104
	v_add_f32_e32 v88, v90, v88
	v_exp_f32_e32 v96, v84
	v_add_f32_e32 v84, v91, v88
	v_add_f32_e32 v84, v94, v84
	v_add_f32_e32 v84, v95, v84
	v_sub_f32_e32 v80, v80, v104
	v_add_f32_e32 v86, v96, v84
	v_exp_f32_e32 v84, v80
	v_sub_f32_e32 v80, v81, v104
	v_exp_f32_e32 v85, v80
	v_sub_f32_e32 v80, v82, v104
	v_exp_f32_e32 v81, v80
	v_sub_f32_e32 v80, v83, v104
	v_exp_f32_e32 v82, v80
	v_sub_f32_e32 v76, v76, v104
	v_add_f32_e32 v80, v84, v86
	v_exp_f32_e32 v83, v76
	v_sub_f32_e32 v76, v77, v104
	v_add_f32_e32 v80, v85, v80
	v_exp_f32_e32 v86, v76
	v_sub_f32_e32 v76, v78, v104
	v_add_f32_e32 v80, v81, v80
	v_exp_f32_e32 v87, v76
	v_sub_f32_e32 v76, v79, v104
	v_add_f32_e32 v80, v82, v80
	v_exp_f32_e32 v88, v76
	v_add_f32_e32 v76, v83, v80
	v_add_f32_e32 v76, v86, v76
	v_add_f32_e32 v76, v87, v76
	v_sub_f32_e32 v68, v68, v104
	v_add_f32_e32 v78, v88, v76
	v_exp_f32_e32 v76, v68
	v_sub_f32_e32 v68, v69, v104
	v_exp_f32_e32 v77, v68
	v_sub_f32_e32 v68, v70, v104
	v_exp_f32_e32 v68, v68
	v_sub_f32_e32 v69, v71, v104
	v_exp_f32_e32 v69, v69
	v_sub_f32_e32 v64, v64, v104
	v_add_f32_e32 v70, v76, v78
	v_exp_f32_e32 v71, v64
	v_sub_f32_e32 v64, v65, v104
	v_add_f32_e32 v70, v77, v70
	v_exp_f32_e32 v78, v64
	v_sub_f32_e32 v64, v66, v104
	v_add_f32_e32 v70, v68, v70
	v_exp_f32_e32 v79, v64
	v_sub_f32_e32 v64, v67, v104
	v_add_f32_e32 v70, v69, v70
	v_exp_f32_e32 v80, v64
	v_add_f32_e32 v64, v71, v70
	v_add_f32_e32 v64, v78, v64
	v_add_f32_e32 v64, v79, v64
	v_add_f32_e32 v70, v80, v64
	v_sub_f32_e32 v64, v72, v104
	v_exp_f32_e32 v65, v64
	v_sub_f32_e32 v64, v73, v104
	v_exp_f32_e32 v67, v64
	v_sub_f32_e32 v64, v74, v104
	v_exp_f32_e32 v64, v64
	v_sub_f32_e32 v66, v75, v104
	v_exp_f32_e32 v66, v66
	v_sub_f32_e32 v60, v60, v104
	v_add_f32_e32 v70, v65, v70
	v_exp_f32_e32 v60, v60
	v_sub_f32_e32 v61, v61, v104
	v_add_f32_e32 v70, v67, v70
	v_exp_f32_e32 v61, v61
	v_sub_f32_e32 v62, v62, v104
	v_add_f32_e32 v70, v64, v70
	v_exp_f32_e32 v62, v62
	v_sub_f32_e32 v63, v63, v104
	v_add_f32_e32 v70, v66, v70
	v_exp_f32_e32 v63, v63
	v_add_f32_e32 v70, v60, v70
	v_add_f32_e32 v70, v61, v70
	v_add_f32_e32 v70, v62, v70
	v_add_f32_e32 v75, v63, v70
	v_sub_f32_e32 v56, v56, v104
	v_add_u32_e32 v70, v133, v115
	v_add_u32_e32 v73, 0x9000, v70
	v_add_u32_e32 v72, 0x9000, v137
	v_add_u32_e32 v70, 0xb000, v137
	v_exp_f32_e32 v74, v56
	v_add_u32_e32 v56, 0xd000, v137
	v_cvt_pk_bf16_f32 v106, v106, v107
	v_cvt_pk_bf16_f32 v107, v108, v110
	v_cvt_pk_bf16_f32 v108, v109, v111
	v_cvt_pk_bf16_f32 v109, v138, v139
	s_nop 1
	v_mfma_f32_16x16x32_bf16 v[138:141], v[204:207], v[106:109], 0
	ds_read_b128 v[200:203], v240 offset:128
	v_cvt_pk_bf16_f32 v100, v100, v101
	v_cvt_pk_bf16_f32 v101, v97, v98
	v_cvt_pk_bf16_f32 v102, v99, v102
	v_mfma_f32_16x16x32_bf16 v[142:145], v[212:215], v[106:109], 0
	ds_read_b128 v[204:207], v242 offset:384
	v_cvt_pk_bf16_f32 v103, v103, v105
	v_cvt_pk_bf16_f32 v92, v92, v93
	v_mfma_f32_16x16x32_bf16 v[146:149], v[216:219], v[106:109], 0
	ds_read_b128 v[212:215], v241 offset:128
	v_cvt_pk_bf16_f32 v93, v89, v90
	v_cvt_pk_bf16_f32 v94, v91, v94
	v_cvt_pk_bf16_f32 v95, v95, v96
	v_mfma_f32_16x16x32_bf16 v[106:109], v[220:223], v[106:109], 0
	ds_read_b128 v[216:219], v245 offset:640
	v_cvt_pk_bf16_f32 v84, v84, v85
	v_cvt_pk_bf16_f32 v85, v81, v82
	v_mfma_f32_16x16x32_bf16 v[138:141], v[208:211], v[100:103], v[138:141]
	ds_read_b128 v[220:223], v240 offset:192
	v_cvt_pk_bf16_f32 v86, v83, v86
	v_cvt_pk_bf16_f32 v87, v87, v88
	v_mfma_f32_16x16x32_bf16 v[142:145], v[196:199], v[100:103], v[142:145]
	ds_read_b128 v[208:211], v242 offset:448
	v_sub_f32_e32 v57, v57, v104
	v_cvt_pk_bf16_f32 v76, v76, v77
	v_mfma_f32_16x16x32_bf16 v[146:149], v[172:175], v[100:103], v[146:149]
	ds_read_b128 v[196:199], v241 offset:192
	v_cvt_pk_bf16_f32 v77, v68, v69
	v_cvt_pk_bf16_f32 v78, v71, v78
	v_cvt_pk_bf16_f32 v79, v79, v80
	v_mfma_f32_16x16x32_bf16 v[98:101], v[176:179], v[100:103], v[106:109]
	ds_read_b128 v[172:175], v245 offset:704
	v_exp_f32_e32 v57, v57
	v_sub_f32_e32 v58, v58, v104
	s_waitcnt lgkmcnt(7)
	v_mfma_f32_16x16x32_bf16 v[138:141], v[200:203], v[92:95], v[138:141]
	ds_read_b128 v[176:179], v240 offset:256
	v_exp_f32_e32 v58, v58
	v_sub_f32_e32 v59, v59, v104
	s_waitcnt lgkmcnt(6)
	v_mfma_f32_16x16x32_bf16 v[106:109], v[212:215], v[92:95], v[142:145]
	ds_read_b128 v[200:203], v242 offset:512
	v_exp_f32_e32 v59, v59
	v_sub_f32_e32 v52, v52, v104
	v_add_f32_e32 v75, v74, v75
	v_mfma_f32_16x16x32_bf16 v[142:145], v[204:207], v[92:95], v[146:149]
	ds_read_b128 v[212:215], v241 offset:256
	v_exp_f32_e32 v52, v52
	v_sub_f32_e32 v53, v53, v104
	v_add_f32_e32 v75, v57, v75
	s_waitcnt lgkmcnt(7)
	v_mfma_f32_16x16x32_bf16 v[90:93], v[216:219], v[92:95], v[98:101]
	ds_read_b128 v[204:207], v245 offset:768
	v_exp_f32_e32 v53, v53
	v_sub_f32_e32 v54, v54, v104
	s_waitcnt lgkmcnt(7)
	v_mfma_f32_16x16x32_bf16 v[138:141], v[220:223], v[84:87], v[138:141]
	ds_read_b128 v[216:219], v241 offset:320
	v_add_f32_e32 v75, v58, v75
	v_exp_f32_e32 v54, v54
	s_waitcnt lgkmcnt(6)
	v_mfma_f32_16x16x32_bf16 v[94:97], v[196:199], v[84:87], v[106:109]
	ds_read_b128 v[220:223], v245 offset:832
	v_sub_f32_e32 v55, v55, v104
	v_add_f32_e32 v75, v59, v75
	v_exp_f32_e32 v55, v55
	v_mfma_f32_16x16x32_bf16 v[98:101], v[208:211], v[84:87], v[142:145]
	ds_read_b128 v[196:199], v242 offset:576
	v_sub_f32_e32 v48, v48, v104
	v_add_f32_e32 v75, v52, v75
	v_exp_f32_e32 v102, v48
	s_waitcnt lgkmcnt(7)
	v_mfma_f32_16x16x32_bf16 v[82:85], v[172:175], v[84:87], v[90:93]
	ds_read_b128 v[208:211], v240 offset:320
	v_sub_f32_e32 v48, v49, v104
	v_add_f32_e32 v75, v53, v75
	s_waitcnt lgkmcnt(7)
	v_mfma_f32_16x16x32_bf16 v[106:109], v[176:179], v[76:79], v[138:141]
	ds_read_b128 v[172:175], v240 offset:384
	v_exp_f32_e32 v103, v48
	v_sub_f32_e32 v48, v50, v104
	v_add_f32_e32 v75, v54, v75
	s_waitcnt lgkmcnt(6)
	v_mfma_f32_16x16x32_bf16 v[86:89], v[212:215], v[76:79], v[94:97]
	ds_read_b128 v[176:179], v242 offset:640
	v_exp_f32_e32 v68, v48
	v_add_f32_e32 v75, v55, v75
	v_cvt_pk_bf16_f32 v80, v65, v67
	v_mfma_f32_16x16x32_bf16 v[90:93], v[200:203], v[76:79], v[98:101]
	ds_read_b128 v[212:215], v241 offset:384
	v_cvt_pk_bf16_f32 v81, v64, v66
	s_waitcnt lgkmcnt(7)
	v_mfma_f32_16x16x32_bf16 v[76:79], v[204:207], v[76:79], v[82:85]
	ds_read_b128 v[200:203], v245 offset:896
	v_cvt_pk_bf16_f32 v82, v60, v61
	v_cvt_pk_bf16_f32 v83, v62, v63
	v_add_f32_e32 v48, v102, v75
	v_add_f32_e32 v48, v103, v48
	v_add_f32_e32 v69, v68, v48
	v_sub_f32_e32 v71, v51, v104
	s_waitcnt lgkmcnt(7)
	v_mfma_f32_16x16x32_bf16 v[84:87], v[216:219], v[80:83], v[86:89]
	ds_read_b128 v[204:207], v240 offset:448
	v_exp_f32_e32 v71, v71
	v_sub_f32_e32 v44, v44, v104
	v_exp_f32_e32 v94, v44
	s_waitcnt lgkmcnt(6)
	v_mfma_f32_16x16x32_bf16 v[60:63], v[196:199], v[80:83], v[90:93]
	ds_read_b128 v[216:219], v242 offset:704
	v_sub_f32_e32 v44, v45, v104
	v_exp_f32_e32 v95, v44
	v_sub_f32_e32 v45, v46, v104
	v_mfma_f32_16x16x32_bf16 v[64:67], v[220:223], v[80:83], v[76:79]
	ds_read_b128 v[196:199], v241 offset:448
	v_cvt_pk_bf16_f32 v76, v52, v53
	v_cvt_pk_bf16_f32 v77, v54, v55
	s_waitcnt lgkmcnt(7)
	v_mfma_f32_16x16x32_bf16 v[48:51], v[208:211], v[80:83], v[106:109]
	ds_read_b128 v[220:223], v245 offset:960
	v_add_f32_e32 v69, v71, v69
	v_cvt_pk_bf16_f32 v74, v74, v57
	v_exp_f32_e32 v57, v45
	v_sub_f32_e32 v45, v47, v104
	v_add_f32_e32 v44, v94, v69
	v_exp_f32_e32 v69, v45
	v_add_f32_e32 v44, v95, v44
	v_cvt_pk_bf16_f32 v75, v58, v59
	s_nop 0
	v_add_f32_e32 v58, v57, v44
	s_waitcnt lgkmcnt(7)
	v_mfma_f32_16x16x32_bf16 v[48:51], v[172:175], v[74:77], v[48:51]
	s_waitcnt lgkmcnt(6)
	v_mfma_f32_16x16x32_bf16 v[44:47], v[176:179], v[74:77], v[60:63]
	v_add_f32_e32 v73, v69, v58
	ds_bpermute_b32 v82, v128, v73
	v_cvt_pk_bf16_f32 v69, v57, v69
	s_waitcnt lgkmcnt(6)
	v_mfma_f32_16x16x32_bf16 v[78:81], v[212:215], v[74:77], v[84:87]
	s_waitcnt lgkmcnt(0)
	v_add_f32_e32 v57, v73, v82
	v_mfma_f32_16x16x32_bf16 v[58:61], v[200:203], v[74:77], v[64:67]
	ds_bpermute_b32 v74, v113, v57
	v_cvt_pk_bf16_f32 v66, v102, v103
	v_cvt_pk_bf16_f32 v67, v68, v71
	v_cvt_pk_bf16_f32 v68, v94, v95
	s_nop 0
	v_mfma_f32_16x16x32_bf16 v[48:51], v[204:207], v[66:69], v[48:51]
	s_waitcnt lgkmcnt(0)
	v_add_f32_e32 v56, v57, v74
	v_rcp_f32_e32 v56, v56
	v_mfma_f32_16x16x32_bf16 v[62:65], v[196:199], v[66:69], v[78:81]
	s_nop 3
	v_mul_f32_e64 v50, v56, v50
	v_mul_f32_e64 v51, v56, v51
	v_pk_mul_f32 v[48:49], v[56:57], v[48:49] op_sel_hi:[0,1]
	v_mfma_f32_16x16x32_bf16 v[44:47], v[216:219], v[66:69], v[44:47]
	v_mfma_f32_16x16x32_bf16 v[52:55], v[220:223], v[66:69], v[58:61]
	s_nop 2
	v_mul_f32_e64 v58, v50, v50
	v_mul_f32_e64 v59, v51, v51
	v_pk_mul_f32 v[60:61], v[48:49], v[48:49]
	v_cvt_pk_bf16_f32 v48, v48, v49
	v_cvt_pk_bf16_f32 v49, v50, v51
	s_nop 0
	v_pk_mov_b32 v[66:67], v[60:61], v[58:59] op_sel:[1,0]
	v_mov_b32_e32 v61, v59
	v_pk_add_f32 v[58:59], v[66:67], v[60:61]
	s_nop 0
	v_add_f32_e32 v57, v58, v59
	v_pk_mul_f32 v[50:51], v[56:57], v[64:65] op_sel_hi:[0,1]
	v_pk_mul_f32 v[60:61], v[56:57], v[62:63] op_sel_hi:[0,1]
	v_pk_mul_f32 v[62:63], v[50:51], v[50:51]
	v_pk_mul_f32 v[64:65], v[60:61], v[60:61]
	v_pk_mul_f32 v[52:53], v[56:57], v[52:53] op_sel_hi:[0,1]
	v_pk_mov_b32 v[66:67], v[64:65], v[62:63] op_sel:[1,0]
	v_mov_b32_e32 v65, v63
	v_pk_add_f32 v[62:63], v[66:67], v[64:65]
	v_cvt_pk_bf16_f32 v60, v60, v61
	v_cvt_pk_bf16_f32 v61, v50, v51
	v_pk_mul_f32 v[46:47], v[56:57], v[46:47] op_sel_hi:[0,1]
	v_pk_mul_f32 v[44:45], v[56:57], v[44:45] op_sel_hi:[0,1]
	v_pk_mul_f32 v[50:51], v[56:57], v[54:55] op_sel_hi:[0,1]
	v_mul_f32_e32 v56, v53, v53
	v_pk_add_f32 v[54:55], v[62:63], v[62:63] op_sel:[0,1] op_sel_hi:[1,0]
	v_add_f32_e32 v58, v130, v57
	v_mul_f32_e32 v57, v50, v50
	v_mov_b32_e32 v55, v56
	v_mul_f32_e32 v56, v45, v45
	ds_write2_b64 v134, v[48:49], v[60:61] offset1:4
	v_cvt_pk_bf16_f32 v48, v44, v45
	v_pk_fma_f32 v[44:45], v[44:45], v[44:45], v[56:57] op_sel_hi:[1,1,0]
	v_mul_f32_e32 v56, v47, v47
	v_cvt_pk_bf16_f32 v49, v46, v47
	v_mul_f32_e32 v60, v51, v51
	v_pk_fma_f32 v[46:47], v[46:47], v[46:47], v[56:57] op_sel_hi:[1,1,0]
	v_mul_f32_e32 v59, v52, v52
	v_mov_b32_e32 v45, v57
	v_mov_b32_e32 v47, v60
	v_pk_add_f32 v[54:55], v[58:59], v[54:55]
	v_pk_add_f32 v[44:45], v[44:45], v[46:47]
	s_nop 0
	v_pk_add_f32 v[44:45], v[54:55], v[44:45]
	s_nop 0
	v_add_f32_e32 v130, v44, v45
	v_cvt_pk_bf16_f32 v44, v52, v53
	v_cvt_pk_bf16_f32 v45, v50, v51
	ds_write2_b64 v134, v[48:49], v[44:45] offset0:8 offset1:12
	v_add_u32_e32 v134, 0x80, v134
	s_cbranch_scc0 .LBB0_215

	.amdhsa_kernel _Z6k_mega6Params
		.amdhsa_group_segment_fixed_size 0
		.amdhsa_private_segment_fixed_size 0
		.amdhsa_kernarg_size 432
		.amdhsa_user_sgpr_count 2
		.amdhsa_user_sgpr_dispatch_ptr 0
		.amdhsa_user_sgpr_queue_ptr 0
		.amdhsa_user_sgpr_kernarg_segment_ptr 1
		.amdhsa_user_sgpr_dispatch_id 0
		.amdhsa_user_sgpr_kernarg_preload_length 0
		.amdhsa_user_sgpr_kernarg_preload_offset 0
		.amdhsa_user_sgpr_private_segment_size 0
		.amdhsa_uses_dynamic_stack 0
		.amdhsa_enable_private_segment 0
		.amdhsa_system_sgpr_workgroup_id_x 1
		.amdhsa_system_sgpr_workgroup_id_y 0
		.amdhsa_system_sgpr_workgroup_id_z 0
		.amdhsa_system_sgpr_workgroup_info 0
		.amdhsa_system_vgpr_workitem_id 0
		.amdhsa_next_free_vgpr 256
		.amdhsa_next_free_sgpr 100
		.amdhsa_accum_offset 256
		.amdhsa_reserve_vcc 1
		.amdhsa_float_round_mode_32 0
		.amdhsa_float_round_mode_16_64 0
		.amdhsa_float_denorm_mode_32 3
		.amdhsa_float_denorm_mode_16_64 3
		.amdhsa_dx10_clamp 1
		.amdhsa_ieee_mode 1
		.amdhsa_fp16_overflow 0
		.amdhsa_tg_split 0
		.amdhsa_exception_fp_ieee_invalid_op 0
		.amdhsa_exception_fp_denorm_src 0
		.amdhsa_exception_fp_ieee_div_zero 0
		.amdhsa_exception_fp_ieee_overflow 0
		.amdhsa_exception_fp_ieee_underflow 0
		.amdhsa_exception_fp_ieee_inexact 0
		.amdhsa_exception_int_div_zero 0
	.end_amdhsa_kernel

amdhsa.kernels:
  - .agpr_count:     0
    .args:
      - .offset:         0
        .size:           176
        .value_kind:     by_value
      - .offset:         176
        .size:           4
        .value_kind:     hidden_block_count_x
      - .offset:         180
        .size:           4
        .value_kind:     hidden_block_count_y
      - .offset:         184
        .size:           4
        .value_kind:     hidden_block_count_z
      - .offset:         188
        .size:           2
        .value_kind:     hidden_group_size_x
      - .offset:         190
        .size:           2
        .value_kind:     hidden_group_size_y
      - .offset:         192
        .size:           2
        .value_kind:     hidden_group_size_z
      - .offset:         194
        .size:           2
        .value_kind:     hidden_remainder_x
      - .offset:         196
        .size:           2
        .value_kind:     hidden_remainder_y
      - .offset:         198
        .size:           2
        .value_kind:     hidden_remainder_z
      - .offset:         216
        .size:           8
        .value_kind:     hidden_global_offset_x
      - .offset:         224
        .size:           8
        .value_kind:     hidden_global_offset_y
      - .offset:         232
        .size:           8
        .value_kind:     hidden_global_offset_z
      - .offset:         240
        .size:           2
        .value_kind:     hidden_grid_dims
      - .offset:         296
        .size:           4
        .value_kind:     hidden_dynamic_lds_size
    .group_segment_fixed_size: 0
    .kernarg_segment_align: 8
    .kernarg_segment_size: 432
    .language:       OpenCL C
    .language_version:
      - 2
      - 0
    .max_flat_workgroup_size: 512
    .name:           _Z6k_mega6Params
    .private_segment_fixed_size: 0
    .sgpr_count:     106
    .sgpr_spill_count: 101
    .symbol:         _Z6k_mega6Params.kd
    .uniform_work_group_size: 1
    .uses_dynamic_stack: false
    .vgpr_count:     256
    .vgpr_spill_count: 0
    .wavefront_size: 64
